# LoRA GEMM epilogue rewritten: class per unit, w0/a0 vectors loaded once, straight-line math in the same op order
# speedup vs baseline: 1.0685x; 1.0060x over previous
.LBB0_872:
	s_or_b64 exec, exec, s[0:1]
	s_add_u32 s18, s6, 0x5200000
	s_addc_u32 s19, s7, 0
	s_add_u32 s4, s6, 0x6200000
	s_addc_u32 s5, s7, 0
	v_readlane_b32 s0, v254, 31
	s_add_u32 s16, s6, 0x7200000
	v_readlane_b32 s1, v254, 32
	s_addc_u32 s17, s7, 0
	s_lshl_b64 s[20:21], s[0:1], 2
	s_add_u32 s0, s11, s20
	s_addc_u32 s1, s12, s21
	s_add_u32 s14, s13, s20
	s_addc_u32 s15, s15, s21
	v_lshl_or_b32 v129, s9, 8, v133
	s_and_b32 s24, 0xffff, s8
	v_lshl_add_u32 v130, v130, 6, v129
	v_lshlrev_b32_e32 v129, 5, v131
	v_lshlrev_b32_e32 v131, 2, v132
	v_or3_b32 v129, v129, v131, s10
	v_lshlrev_b32_e32 v131, 10, v130
	v_lshl_add_u32 v131, v129, 1, v131
	v_lshlrev_b32_e32 v133, 2, v129
	v_add_u32_e32 v134, 0x4000, v131
	v_add_u32_e32 v135, 0x8000, v131
	v_add_u32_e32 v136, 0xc000, v131
	v_add_u32_e32 v137, 0x20000, v131
	v_add_u32_e32 v138, 0x24000, v131
	v_add_u32_e32 v139, 0x28000, v131
	v_add_u32_e32 v140, 0x2c000, v131
	s_cmp_gt_u32 s24, 3
	s_cbranch_scc1 .Llora_g
	s_cmp_gt_u32 s24, 1
	s_cbranch_scc1 .Llora_a
	global_load_dwordx4 v[142:145], v133, s[0:1]
	global_load_dwordx4 v[146:149], v133, s[0:1] offset:64
	global_load_dwordx4 v[150:153], v133, s[0:1] offset:512
	global_load_dwordx4 v[154:157], v133, s[0:1] offset:576
	s_waitcnt vmcnt(0)
	v_add_f32_e32 v124, v124, v142
	v_add_f32_e32 v125, v125, v143
	v_add_f32_e32 v126, v126, v144
	v_add_f32_e32 v127, v127, v145
	v_mul_f32_e32 v124, 0xbfb8aa3b, v124
	v_mul_f32_e32 v125, 0xbfb8aa3b, v125
	v_mul_f32_e32 v126, 0xbfb8aa3b, v126
	v_mul_f32_e32 v127, 0xbfb8aa3b, v127
	v_exp_f32_e32 v124, v124
	v_exp_f32_e32 v125, v125
	v_exp_f32_e32 v126, v126
	v_exp_f32_e32 v127, v127
	v_add_f32_e32 v124, 1.0, v124
	v_add_f32_e32 v125, 1.0, v125
	v_add_f32_e32 v126, 1.0, v126
	v_add_f32_e32 v127, 1.0, v127
	v_rcp_f32_e32 v124, v124
	v_rcp_f32_e32 v125, v125
	v_rcp_f32_e32 v126, v126
	v_rcp_f32_e32 v127, v127
	v_mul_f32_e32 v124, 0xbf1b4598, v124
	v_mul_f32_e32 v125, 0xbf1b4598, v125
	v_mul_f32_e32 v126, 0xbf1b4598, v126
	v_mul_f32_e32 v127, 0xbf1b4598, v127
	v_mul_f32_e32 v124, 0x3fb8aa3b, v124
	v_mul_f32_e32 v125, 0x3fb8aa3b, v125
	v_mul_f32_e32 v126, 0x3fb8aa3b, v126
	v_mul_f32_e32 v127, 0x3fb8aa3b, v127
	v_exp_f32_e32 v124, v124
	v_exp_f32_e32 v125, v125
	v_exp_f32_e32 v126, v126
	v_exp_f32_e32 v127, v127
	s_nop 0
	v_cvt_pk_f16_f32 v124, v124, v125
	v_cvt_pk_f16_f32 v125, v126, v127
	global_store_dwordx2 v131, v[124:125], s[18:19]
	v_add_f32_e32 v120, v120, v146
	v_add_f32_e32 v121, v121, v147
	v_add_f32_e32 v122, v122, v148
	v_add_f32_e32 v123, v123, v149
	v_mul_f32_e32 v120, 0xbfb8aa3b, v120
	v_mul_f32_e32 v121, 0xbfb8aa3b, v121
	v_mul_f32_e32 v122, 0xbfb8aa3b, v122
	v_mul_f32_e32 v123, 0xbfb8aa3b, v123
	v_exp_f32_e32 v120, v120
	v_exp_f32_e32 v121, v121
	v_exp_f32_e32 v122, v122
	v_exp_f32_e32 v123, v123
	v_add_f32_e32 v120, 1.0, v120
	v_add_f32_e32 v121, 1.0, v121
	v_add_f32_e32 v122, 1.0, v122
	v_add_f32_e32 v123, 1.0, v123
	v_rcp_f32_e32 v120, v120
	v_rcp_f32_e32 v121, v121
	v_rcp_f32_e32 v122, v122
	v_rcp_f32_e32 v123, v123
	v_mul_f32_e32 v120, 0xbf1b4598, v120
	v_mul_f32_e32 v121, 0xbf1b4598, v121
	v_mul_f32_e32 v122, 0xbf1b4598, v122
	v_mul_f32_e32 v123, 0xbf1b4598, v123
	v_mul_f32_e32 v120, 0x3fb8aa3b, v120
	v_mul_f32_e32 v121, 0x3fb8aa3b, v121
	v_mul_f32_e32 v122, 0x3fb8aa3b, v122
	v_mul_f32_e32 v123, 0x3fb8aa3b, v123
	v_exp_f32_e32 v120, v120
	v_exp_f32_e32 v121, v121
	v_exp_f32_e32 v122, v122
	v_exp_f32_e32 v123, v123
	s_nop 0
	v_cvt_pk_f16_f32 v120, v120, v121
	v_cvt_pk_f16_f32 v121, v122, v123
	global_store_dwordx2 v131, v[120:121], s[18:19] offset:32
	v_add_f32_e32 v116, v116, v142
	v_add_f32_e32 v117, v117, v143
	v_add_f32_e32 v118, v118, v144
	v_add_f32_e32 v119, v119, v145
	v_mul_f32_e32 v116, 0xbfb8aa3b, v116
	v_mul_f32_e32 v117, 0xbfb8aa3b, v117
	v_mul_f32_e32 v118, 0xbfb8aa3b, v118
	v_mul_f32_e32 v119, 0xbfb8aa3b, v119
	v_exp_f32_e32 v116, v116
	v_exp_f32_e32 v117, v117
	v_exp_f32_e32 v118, v118
	v_exp_f32_e32 v119, v119
	v_add_f32_e32 v116, 1.0, v116
	v_add_f32_e32 v117, 1.0, v117
	v_add_f32_e32 v118, 1.0, v118
	v_add_f32_e32 v119, 1.0, v119
	v_rcp_f32_e32 v116, v116
	v_rcp_f32_e32 v117, v117
	v_rcp_f32_e32 v118, v118
	v_rcp_f32_e32 v119, v119
	v_mul_f32_e32 v116, 0xbf1b4598, v116
	v_mul_f32_e32 v117, 0xbf1b4598, v117
	v_mul_f32_e32 v118, 0xbf1b4598, v118
	v_mul_f32_e32 v119, 0xbf1b4598, v119
	v_mul_f32_e32 v116, 0x3fb8aa3b, v116
	v_mul_f32_e32 v117, 0x3fb8aa3b, v117
	v_mul_f32_e32 v118, 0x3fb8aa3b, v118
	v_mul_f32_e32 v119, 0x3fb8aa3b, v119
	v_exp_f32_e32 v116, v116
	v_exp_f32_e32 v117, v117
	v_exp_f32_e32 v118, v118
	v_exp_f32_e32 v119, v119
	s_nop 0
	v_cvt_pk_f16_f32 v116, v116, v117
	v_cvt_pk_f16_f32 v117, v118, v119
	global_store_dwordx2 v134, v[116:117], s[18:19]
	v_add_f32_e32 v112, v112, v146
	v_add_f32_e32 v113, v113, v147
	v_add_f32_e32 v114, v114, v148
	v_add_f32_e32 v115, v115, v149
	v_mul_f32_e32 v112, 0xbfb8aa3b, v112
	v_mul_f32_e32 v113, 0xbfb8aa3b, v113
	v_mul_f32_e32 v114, 0xbfb8aa3b, v114
	v_mul_f32_e32 v115, 0xbfb8aa3b, v115
	v_exp_f32_e32 v112, v112
	v_exp_f32_e32 v113, v113
	v_exp_f32_e32 v114, v114
	v_exp_f32_e32 v115, v115
	v_add_f32_e32 v112, 1.0, v112
	v_add_f32_e32 v113, 1.0, v113
	v_add_f32_e32 v114, 1.0, v114
	v_add_f32_e32 v115, 1.0, v115
	v_rcp_f32_e32 v112, v112
	v_rcp_f32_e32 v113, v113
	v_rcp_f32_e32 v114, v114
	v_rcp_f32_e32 v115, v115
	v_mul_f32_e32 v112, 0xbf1b4598, v112
	v_mul_f32_e32 v113, 0xbf1b4598, v113
	v_mul_f32_e32 v114, 0xbf1b4598, v114
	v_mul_f32_e32 v115, 0xbf1b4598, v115
	v_mul_f32_e32 v112, 0x3fb8aa3b, v112
	v_mul_f32_e32 v113, 0x3fb8aa3b, v113
	v_mul_f32_e32 v114, 0x3fb8aa3b, v114
	v_mul_f32_e32 v115, 0x3fb8aa3b, v115
	v_exp_f32_e32 v112, v112
	v_exp_f32_e32 v113, v113
	v_exp_f32_e32 v114, v114
	v_exp_f32_e32 v115, v115
	s_nop 0
	v_cvt_pk_f16_f32 v112, v112, v113
	v_cvt_pk_f16_f32 v113, v114, v115
	global_store_dwordx2 v134, v[112:113], s[18:19] offset:32
	v_add_f32_e32 v108, v108, v142
	v_add_f32_e32 v109, v109, v143
	v_add_f32_e32 v110, v110, v144
	v_add_f32_e32 v111, v111, v145
	v_mul_f32_e32 v108, 0xbfb8aa3b, v108
	v_mul_f32_e32 v109, 0xbfb8aa3b, v109
	v_mul_f32_e32 v110, 0xbfb8aa3b, v110
	v_mul_f32_e32 v111, 0xbfb8aa3b, v111
	v_exp_f32_e32 v108, v108
	v_exp_f32_e32 v109, v109
	v_exp_f32_e32 v110, v110
	v_exp_f32_e32 v111, v111
	v_add_f32_e32 v108, 1.0, v108
	v_add_f32_e32 v109, 1.0, v109
	v_add_f32_e32 v110, 1.0, v110
	v_add_f32_e32 v111, 1.0, v111
	v_rcp_f32_e32 v108, v108
	v_rcp_f32_e32 v109, v109
	v_rcp_f32_e32 v110, v110
	v_rcp_f32_e32 v111, v111
	v_mul_f32_e32 v108, 0xbf1b4598, v108
	v_mul_f32_e32 v109, 0xbf1b4598, v109
	v_mul_f32_e32 v110, 0xbf1b4598, v110
	v_mul_f32_e32 v111, 0xbf1b4598, v111
	v_mul_f32_e32 v108, 0x3fb8aa3b, v108
	v_mul_f32_e32 v109, 0x3fb8aa3b, v109
	v_mul_f32_e32 v110, 0x3fb8aa3b, v110
	v_mul_f32_e32 v111, 0x3fb8aa3b, v111
	v_exp_f32_e32 v108, v108
	v_exp_f32_e32 v109, v109
	v_exp_f32_e32 v110, v110
	v_exp_f32_e32 v111, v111
	s_nop 0
	v_cvt_pk_f16_f32 v108, v108, v109
	v_cvt_pk_f16_f32 v109, v110, v111
	global_store_dwordx2 v135, v[108:109], s[18:19]
	v_add_f32_e32 v104, v104, v146
	v_add_f32_e32 v105, v105, v147
	v_add_f32_e32 v106, v106, v148
	v_add_f32_e32 v107, v107, v149
	v_mul_f32_e32 v104, 0xbfb8aa3b, v104
	v_mul_f32_e32 v105, 0xbfb8aa3b, v105
	v_mul_f32_e32 v106, 0xbfb8aa3b, v106
	v_mul_f32_e32 v107, 0xbfb8aa3b, v107
	v_exp_f32_e32 v104, v104
	v_exp_f32_e32 v105, v105
	v_exp_f32_e32 v106, v106
	v_exp_f32_e32 v107, v107
	v_add_f32_e32 v104, 1.0, v104
	v_add_f32_e32 v105, 1.0, v105
	v_add_f32_e32 v106, 1.0, v106
	v_add_f32_e32 v107, 1.0, v107
	v_rcp_f32_e32 v104, v104
	v_rcp_f32_e32 v105, v105
	v_rcp_f32_e32 v106, v106
	v_rcp_f32_e32 v107, v107
	v_mul_f32_e32 v104, 0xbf1b4598, v104
	v_mul_f32_e32 v105, 0xbf1b4598, v105
	v_mul_f32_e32 v106, 0xbf1b4598, v106
	v_mul_f32_e32 v107, 0xbf1b4598, v107
	v_mul_f32_e32 v104, 0x3fb8aa3b, v104
	v_mul_f32_e32 v105, 0x3fb8aa3b, v105
	v_mul_f32_e32 v106, 0x3fb8aa3b, v106
	v_mul_f32_e32 v107, 0x3fb8aa3b, v107
	v_exp_f32_e32 v104, v104
	v_exp_f32_e32 v105, v105
	v_exp_f32_e32 v106, v106
	v_exp_f32_e32 v107, v107
	s_nop 0
	v_cvt_pk_f16_f32 v104, v104, v105
	v_cvt_pk_f16_f32 v105, v106, v107
	global_store_dwordx2 v135, v[104:105], s[18:19] offset:32
	v_add_f32_e32 v100, v100, v142
	v_add_f32_e32 v101, v101, v143
	v_add_f32_e32 v102, v102, v144
	v_add_f32_e32 v103, v103, v145
	v_mul_f32_e32 v100, 0xbfb8aa3b, v100
	v_mul_f32_e32 v101, 0xbfb8aa3b, v101
	v_mul_f32_e32 v102, 0xbfb8aa3b, v102
	v_mul_f32_e32 v103, 0xbfb8aa3b, v103
	v_exp_f32_e32 v100, v100
	v_exp_f32_e32 v101, v101
	v_exp_f32_e32 v102, v102
	v_exp_f32_e32 v103, v103
	v_add_f32_e32 v100, 1.0, v100
	v_add_f32_e32 v101, 1.0, v101
	v_add_f32_e32 v102, 1.0, v102
	v_add_f32_e32 v103, 1.0, v103
	v_rcp_f32_e32 v100, v100
	v_rcp_f32_e32 v101, v101
	v_rcp_f32_e32 v102, v102
	v_rcp_f32_e32 v103, v103
	v_mul_f32_e32 v100, 0xbf1b4598, v100
	v_mul_f32_e32 v101, 0xbf1b4598, v101
	v_mul_f32_e32 v102, 0xbf1b4598, v102
	v_mul_f32_e32 v103, 0xbf1b4598, v103
	v_mul_f32_e32 v100, 0x3fb8aa3b, v100
	v_mul_f32_e32 v101, 0x3fb8aa3b, v101
	v_mul_f32_e32 v102, 0x3fb8aa3b, v102
	v_mul_f32_e32 v103, 0x3fb8aa3b, v103
	v_exp_f32_e32 v100, v100
	v_exp_f32_e32 v101, v101
	v_exp_f32_e32 v102, v102
	v_exp_f32_e32 v103, v103
	s_nop 0
	v_cvt_pk_f16_f32 v100, v100, v101
	v_cvt_pk_f16_f32 v101, v102, v103
	global_store_dwordx2 v136, v[100:101], s[18:19]
	v_add_f32_e32 v96, v96, v146
	v_add_f32_e32 v97, v97, v147
	v_add_f32_e32 v98, v98, v148
	v_add_f32_e32 v99, v99, v149
	v_mul_f32_e32 v96, 0xbfb8aa3b, v96
	v_mul_f32_e32 v97, 0xbfb8aa3b, v97
	v_mul_f32_e32 v98, 0xbfb8aa3b, v98
	v_mul_f32_e32 v99, 0xbfb8aa3b, v99
	v_exp_f32_e32 v96, v96
	v_exp_f32_e32 v97, v97
	v_exp_f32_e32 v98, v98
	v_exp_f32_e32 v99, v99
	v_add_f32_e32 v96, 1.0, v96
	v_add_f32_e32 v97, 1.0, v97
	v_add_f32_e32 v98, 1.0, v98
	v_add_f32_e32 v99, 1.0, v99
	v_rcp_f32_e32 v96, v96
	v_rcp_f32_e32 v97, v97
	v_rcp_f32_e32 v98, v98
	v_rcp_f32_e32 v99, v99
	v_mul_f32_e32 v96, 0xbf1b4598, v96
	v_mul_f32_e32 v97, 0xbf1b4598, v97
	v_mul_f32_e32 v98, 0xbf1b4598, v98
	v_mul_f32_e32 v99, 0xbf1b4598, v99
	v_mul_f32_e32 v96, 0x3fb8aa3b, v96
	v_mul_f32_e32 v97, 0x3fb8aa3b, v97
	v_mul_f32_e32 v98, 0x3fb8aa3b, v98
	v_mul_f32_e32 v99, 0x3fb8aa3b, v99
	v_exp_f32_e32 v96, v96
	v_exp_f32_e32 v97, v97
	v_exp_f32_e32 v98, v98
	v_exp_f32_e32 v99, v99
	s_nop 0
	v_cvt_pk_f16_f32 v96, v96, v97
	v_cvt_pk_f16_f32 v97, v98, v99
	global_store_dwordx2 v136, v[96:97], s[18:19] offset:32
	v_add_f32_e32 v92, v92, v150
	v_add_f32_e32 v93, v93, v151
	v_add_f32_e32 v94, v94, v152
	v_add_f32_e32 v95, v95, v153
	v_mul_f32_e32 v92, 0xbfb8aa3b, v92
	v_mul_f32_e32 v93, 0xbfb8aa3b, v93
	v_mul_f32_e32 v94, 0xbfb8aa3b, v94
	v_mul_f32_e32 v95, 0xbfb8aa3b, v95
	v_exp_f32_e32 v92, v92
	v_exp_f32_e32 v93, v93
	v_exp_f32_e32 v94, v94
	v_exp_f32_e32 v95, v95
	v_add_f32_e32 v92, 1.0, v92
	v_add_f32_e32 v93, 1.0, v93
	v_add_f32_e32 v94, 1.0, v94
	v_add_f32_e32 v95, 1.0, v95
	v_rcp_f32_e32 v92, v92
	v_rcp_f32_e32 v93, v93
	v_rcp_f32_e32 v94, v94
	v_rcp_f32_e32 v95, v95
	v_mul_f32_e32 v92, 0xbf1b4598, v92
	v_mul_f32_e32 v93, 0xbf1b4598, v93
	v_mul_f32_e32 v94, 0xbf1b4598, v94
	v_mul_f32_e32 v95, 0xbf1b4598, v95
	v_mul_f32_e32 v92, 0x3fb8aa3b, v92
	v_mul_f32_e32 v93, 0x3fb8aa3b, v93
	v_mul_f32_e32 v94, 0x3fb8aa3b, v94
	v_mul_f32_e32 v95, 0x3fb8aa3b, v95
	v_exp_f32_e32 v92, v92
	v_exp_f32_e32 v93, v93
	v_exp_f32_e32 v94, v94
	v_exp_f32_e32 v95, v95
	s_nop 0
	v_cvt_pk_f16_f32 v92, v92, v93
	v_cvt_pk_f16_f32 v93, v94, v95
	global_store_dwordx2 v131, v[92:93], s[18:19] offset:256
	v_add_f32_e32 v88, v88, v154
	v_add_f32_e32 v89, v89, v155
	v_add_f32_e32 v90, v90, v156
	v_add_f32_e32 v91, v91, v157
	v_mul_f32_e32 v88, 0xbfb8aa3b, v88
	v_mul_f32_e32 v89, 0xbfb8aa3b, v89
	v_mul_f32_e32 v90, 0xbfb8aa3b, v90
	v_mul_f32_e32 v91, 0xbfb8aa3b, v91
	v_exp_f32_e32 v88, v88
	v_exp_f32_e32 v89, v89
	v_exp_f32_e32 v90, v90
	v_exp_f32_e32 v91, v91
	v_add_f32_e32 v88, 1.0, v88
	v_add_f32_e32 v89, 1.0, v89
	v_add_f32_e32 v90, 1.0, v90
	v_add_f32_e32 v91, 1.0, v91
	v_rcp_f32_e32 v88, v88
	v_rcp_f32_e32 v89, v89
	v_rcp_f32_e32 v90, v90
	v_rcp_f32_e32 v91, v91
	v_mul_f32_e32 v88, 0xbf1b4598, v88
	v_mul_f32_e32 v89, 0xbf1b4598, v89
	v_mul_f32_e32 v90, 0xbf1b4598, v90
	v_mul_f32_e32 v91, 0xbf1b4598, v91
	v_mul_f32_e32 v88, 0x3fb8aa3b, v88
	v_mul_f32_e32 v89, 0x3fb8aa3b, v89
	v_mul_f32_e32 v90, 0x3fb8aa3b, v90
	v_mul_f32_e32 v91, 0x3fb8aa3b, v91
	v_exp_f32_e32 v88, v88
	v_exp_f32_e32 v89, v89
	v_exp_f32_e32 v90, v90
	v_exp_f32_e32 v91, v91
	s_nop 0
	v_cvt_pk_f16_f32 v88, v88, v89
	v_cvt_pk_f16_f32 v89, v90, v91
	global_store_dwordx2 v131, v[88:89], s[18:19] offset:288
	v_add_f32_e32 v84, v84, v150
	v_add_f32_e32 v85, v85, v151
	v_add_f32_e32 v86, v86, v152
	v_add_f32_e32 v87, v87, v153
	v_mul_f32_e32 v84, 0xbfb8aa3b, v84
	v_mul_f32_e32 v85, 0xbfb8aa3b, v85
	v_mul_f32_e32 v86, 0xbfb8aa3b, v86
	v_mul_f32_e32 v87, 0xbfb8aa3b, v87
	v_exp_f32_e32 v84, v84
	v_exp_f32_e32 v85, v85
	v_exp_f32_e32 v86, v86
	v_exp_f32_e32 v87, v87
	v_add_f32_e32 v84, 1.0, v84
	v_add_f32_e32 v85, 1.0, v85
	v_add_f32_e32 v86, 1.0, v86
	v_add_f32_e32 v87, 1.0, v87
	v_rcp_f32_e32 v84, v84
	v_rcp_f32_e32 v85, v85
	v_rcp_f32_e32 v86, v86
	v_rcp_f32_e32 v87, v87
	v_mul_f32_e32 v84, 0xbf1b4598, v84
	v_mul_f32_e32 v85, 0xbf1b4598, v85
	v_mul_f32_e32 v86, 0xbf1b4598, v86
	v_mul_f32_e32 v87, 0xbf1b4598, v87
	v_mul_f32_e32 v84, 0x3fb8aa3b, v84
	v_mul_f32_e32 v85, 0x3fb8aa3b, v85
	v_mul_f32_e32 v86, 0x3fb8aa3b, v86
	v_mul_f32_e32 v87, 0x3fb8aa3b, v87
	v_exp_f32_e32 v84, v84
	v_exp_f32_e32 v85, v85
	v_exp_f32_e32 v86, v86
	v_exp_f32_e32 v87, v87
	s_nop 0
	v_cvt_pk_f16_f32 v84, v84, v85
	v_cvt_pk_f16_f32 v85, v86, v87
	global_store_dwordx2 v134, v[84:85], s[18:19] offset:256
	v_add_f32_e32 v80, v80, v154
	v_add_f32_e32 v81, v81, v155
	v_add_f32_e32 v82, v82, v156
	v_add_f32_e32 v83, v83, v157
	v_mul_f32_e32 v80, 0xbfb8aa3b, v80
	v_mul_f32_e32 v81, 0xbfb8aa3b, v81
	v_mul_f32_e32 v82, 0xbfb8aa3b, v82
	v_mul_f32_e32 v83, 0xbfb8aa3b, v83
	v_exp_f32_e32 v80, v80
	v_exp_f32_e32 v81, v81
	v_exp_f32_e32 v82, v82
	v_exp_f32_e32 v83, v83
	v_add_f32_e32 v80, 1.0, v80
	v_add_f32_e32 v81, 1.0, v81
	v_add_f32_e32 v82, 1.0, v82
	v_add_f32_e32 v83, 1.0, v83
	v_rcp_f32_e32 v80, v80
	v_rcp_f32_e32 v81, v81
	v_rcp_f32_e32 v82, v82
	v_rcp_f32_e32 v83, v83
	v_mul_f32_e32 v80, 0xbf1b4598, v80
	v_mul_f32_e32 v81, 0xbf1b4598, v81
	v_mul_f32_e32 v82, 0xbf1b4598, v82
	v_mul_f32_e32 v83, 0xbf1b4598, v83
	v_mul_f32_e32 v80, 0x3fb8aa3b, v80
	v_mul_f32_e32 v81, 0x3fb8aa3b, v81
	v_mul_f32_e32 v82, 0x3fb8aa3b, v82
	v_mul_f32_e32 v83, 0x3fb8aa3b, v83
	v_exp_f32_e32 v80, v80
	v_exp_f32_e32 v81, v81
	v_exp_f32_e32 v82, v82
	v_exp_f32_e32 v83, v83
	s_nop 0
	v_cvt_pk_f16_f32 v80, v80, v81
	v_cvt_pk_f16_f32 v81, v82, v83
	global_store_dwordx2 v134, v[80:81], s[18:19] offset:288
	v_add_f32_e32 v76, v76, v150
	v_add_f32_e32 v77, v77, v151
	v_add_f32_e32 v78, v78, v152
	v_add_f32_e32 v79, v79, v153
	v_mul_f32_e32 v76, 0xbfb8aa3b, v76
	v_mul_f32_e32 v77, 0xbfb8aa3b, v77
	v_mul_f32_e32 v78, 0xbfb8aa3b, v78
	v_mul_f32_e32 v79, 0xbfb8aa3b, v79
	v_exp_f32_e32 v76, v76
	v_exp_f32_e32 v77, v77
	v_exp_f32_e32 v78, v78
	v_exp_f32_e32 v79, v79
	v_add_f32_e32 v76, 1.0, v76
	v_add_f32_e32 v77, 1.0, v77
	v_add_f32_e32 v78, 1.0, v78
	v_add_f32_e32 v79, 1.0, v79
	v_rcp_f32_e32 v76, v76
	v_rcp_f32_e32 v77, v77
	v_rcp_f32_e32 v78, v78
	v_rcp_f32_e32 v79, v79
	v_mul_f32_e32 v76, 0xbf1b4598, v76
	v_mul_f32_e32 v77, 0xbf1b4598, v77
	v_mul_f32_e32 v78, 0xbf1b4598, v78
	v_mul_f32_e32 v79, 0xbf1b4598, v79
	v_mul_f32_e32 v76, 0x3fb8aa3b, v76
	v_mul_f32_e32 v77, 0x3fb8aa3b, v77
	v_mul_f32_e32 v78, 0x3fb8aa3b, v78
	v_mul_f32_e32 v79, 0x3fb8aa3b, v79
	v_exp_f32_e32 v76, v76
	v_exp_f32_e32 v77, v77
	v_exp_f32_e32 v78, v78
	v_exp_f32_e32 v79, v79
	s_nop 0
	v_cvt_pk_f16_f32 v76, v76, v77
	v_cvt_pk_f16_f32 v77, v78, v79
	global_store_dwordx2 v135, v[76:77], s[18:19] offset:256
	v_add_f32_e32 v72, v72, v154
	v_add_f32_e32 v73, v73, v155
	v_add_f32_e32 v74, v74, v156
	v_add_f32_e32 v75, v75, v157
	v_mul_f32_e32 v72, 0xbfb8aa3b, v72
	v_mul_f32_e32 v73, 0xbfb8aa3b, v73
	v_mul_f32_e32 v74, 0xbfb8aa3b, v74
	v_mul_f32_e32 v75, 0xbfb8aa3b, v75
	v_exp_f32_e32 v72, v72
	v_exp_f32_e32 v73, v73
	v_exp_f32_e32 v74, v74
	v_exp_f32_e32 v75, v75
	v_add_f32_e32 v72, 1.0, v72
	v_add_f32_e32 v73, 1.0, v73
	v_add_f32_e32 v74, 1.0, v74
	v_add_f32_e32 v75, 1.0, v75
	v_rcp_f32_e32 v72, v72
	v_rcp_f32_e32 v73, v73
	v_rcp_f32_e32 v74, v74
	v_rcp_f32_e32 v75, v75
	v_mul_f32_e32 v72, 0xbf1b4598, v72
	v_mul_f32_e32 v73, 0xbf1b4598, v73
	v_mul_f32_e32 v74, 0xbf1b4598, v74
	v_mul_f32_e32 v75, 0xbf1b4598, v75
	v_mul_f32_e32 v72, 0x3fb8aa3b, v72
	v_mul_f32_e32 v73, 0x3fb8aa3b, v73
	v_mul_f32_e32 v74, 0x3fb8aa3b, v74
	v_mul_f32_e32 v75, 0x3fb8aa3b, v75
	v_exp_f32_e32 v72, v72
	v_exp_f32_e32 v73, v73
	v_exp_f32_e32 v74, v74
	v_exp_f32_e32 v75, v75
	s_nop 0
	v_cvt_pk_f16_f32 v72, v72, v73
	v_cvt_pk_f16_f32 v73, v74, v75
	global_store_dwordx2 v135, v[72:73], s[18:19] offset:288
	v_add_f32_e32 v68, v68, v150
	v_add_f32_e32 v69, v69, v151
	v_add_f32_e32 v70, v70, v152
	v_add_f32_e32 v71, v71, v153
	v_mul_f32_e32 v68, 0xbfb8aa3b, v68
	v_mul_f32_e32 v69, 0xbfb8aa3b, v69
	v_mul_f32_e32 v70, 0xbfb8aa3b, v70
	v_mul_f32_e32 v71, 0xbfb8aa3b, v71
	v_exp_f32_e32 v68, v68
	v_exp_f32_e32 v69, v69
	v_exp_f32_e32 v70, v70
	v_exp_f32_e32 v71, v71
	v_add_f32_e32 v68, 1.0, v68
	v_add_f32_e32 v69, 1.0, v69
	v_add_f32_e32 v70, 1.0, v70
	v_add_f32_e32 v71, 1.0, v71
	v_rcp_f32_e32 v68, v68
	v_rcp_f32_e32 v69, v69
	v_rcp_f32_e32 v70, v70
	v_rcp_f32_e32 v71, v71
	v_mul_f32_e32 v68, 0xbf1b4598, v68
	v_mul_f32_e32 v69, 0xbf1b4598, v69
	v_mul_f32_e32 v70, 0xbf1b4598, v70
	v_mul_f32_e32 v71, 0xbf1b4598, v71
	v_mul_f32_e32 v68, 0x3fb8aa3b, v68
	v_mul_f32_e32 v69, 0x3fb8aa3b, v69
	v_mul_f32_e32 v70, 0x3fb8aa3b, v70
	v_mul_f32_e32 v71, 0x3fb8aa3b, v71
	v_exp_f32_e32 v68, v68
	v_exp_f32_e32 v69, v69
	v_exp_f32_e32 v70, v70
	v_exp_f32_e32 v71, v71
	s_nop 0
	v_cvt_pk_f16_f32 v68, v68, v69
	v_cvt_pk_f16_f32 v69, v70, v71
	global_store_dwordx2 v136, v[68:69], s[18:19] offset:256
	v_add_f32_e32 v64, v64, v154
	v_add_f32_e32 v65, v65, v155
	v_add_f32_e32 v66, v66, v156
	v_add_f32_e32 v67, v67, v157
	v_mul_f32_e32 v64, 0xbfb8aa3b, v64
	v_mul_f32_e32 v65, 0xbfb8aa3b, v65
	v_mul_f32_e32 v66, 0xbfb8aa3b, v66
	v_mul_f32_e32 v67, 0xbfb8aa3b, v67
	v_exp_f32_e32 v64, v64
	v_exp_f32_e32 v65, v65
	v_exp_f32_e32 v66, v66
	v_exp_f32_e32 v67, v67
	v_add_f32_e32 v64, 1.0, v64
	v_add_f32_e32 v65, 1.0, v65
	v_add_f32_e32 v66, 1.0, v66
	v_add_f32_e32 v67, 1.0, v67
	v_rcp_f32_e32 v64, v64
	v_rcp_f32_e32 v65, v65
	v_rcp_f32_e32 v66, v66
	v_rcp_f32_e32 v67, v67
	v_mul_f32_e32 v64, 0xbf1b4598, v64
	v_mul_f32_e32 v65, 0xbf1b4598, v65
	v_mul_f32_e32 v66, 0xbf1b4598, v66
	v_mul_f32_e32 v67, 0xbf1b4598, v67
	v_mul_f32_e32 v64, 0x3fb8aa3b, v64
	v_mul_f32_e32 v65, 0x3fb8aa3b, v65
	v_mul_f32_e32 v66, 0x3fb8aa3b, v66
	v_mul_f32_e32 v67, 0x3fb8aa3b, v67
	v_exp_f32_e32 v64, v64
	v_exp_f32_e32 v65, v65
	v_exp_f32_e32 v66, v66
	v_exp_f32_e32 v67, v67
	s_nop 0
	v_cvt_pk_f16_f32 v64, v64, v65
	v_cvt_pk_f16_f32 v65, v66, v67
	global_store_dwordx2 v136, v[64:65], s[18:19] offset:288
	v_add_f32_e32 v60, v60, v142
	v_add_f32_e32 v61, v61, v143
	v_add_f32_e32 v62, v62, v144
	v_add_f32_e32 v63, v63, v145
	v_mul_f32_e32 v60, 0xbfb8aa3b, v60
	v_mul_f32_e32 v61, 0xbfb8aa3b, v61
	v_mul_f32_e32 v62, 0xbfb8aa3b, v62
	v_mul_f32_e32 v63, 0xbfb8aa3b, v63
	v_exp_f32_e32 v60, v60
	v_exp_f32_e32 v61, v61
	v_exp_f32_e32 v62, v62
	v_exp_f32_e32 v63, v63
	v_add_f32_e32 v60, 1.0, v60
	v_add_f32_e32 v61, 1.0, v61
	v_add_f32_e32 v62, 1.0, v62
	v_add_f32_e32 v63, 1.0, v63
	v_rcp_f32_e32 v60, v60
	v_rcp_f32_e32 v61, v61
	v_rcp_f32_e32 v62, v62
	v_rcp_f32_e32 v63, v63
	v_mul_f32_e32 v60, 0xbf1b4598, v60
	v_mul_f32_e32 v61, 0xbf1b4598, v61
	v_mul_f32_e32 v62, 0xbf1b4598, v62
	v_mul_f32_e32 v63, 0xbf1b4598, v63
	v_mul_f32_e32 v60, 0x3fb8aa3b, v60
	v_mul_f32_e32 v61, 0x3fb8aa3b, v61
	v_mul_f32_e32 v62, 0x3fb8aa3b, v62
	v_mul_f32_e32 v63, 0x3fb8aa3b, v63
	v_exp_f32_e32 v60, v60
	v_exp_f32_e32 v61, v61
	v_exp_f32_e32 v62, v62
	v_exp_f32_e32 v63, v63
	s_nop 0
	v_cvt_pk_f16_f32 v60, v60, v61
	v_cvt_pk_f16_f32 v61, v62, v63
	global_store_dwordx2 v137, v[60:61], s[18:19]
	v_add_f32_e32 v56, v56, v146
	v_add_f32_e32 v57, v57, v147
	v_add_f32_e32 v58, v58, v148
	v_add_f32_e32 v59, v59, v149
	v_mul_f32_e32 v56, 0xbfb8aa3b, v56
	v_mul_f32_e32 v57, 0xbfb8aa3b, v57
	v_mul_f32_e32 v58, 0xbfb8aa3b, v58
	v_mul_f32_e32 v59, 0xbfb8aa3b, v59
	v_exp_f32_e32 v56, v56
	v_exp_f32_e32 v57, v57
	v_exp_f32_e32 v58, v58
	v_exp_f32_e32 v59, v59
	v_add_f32_e32 v56, 1.0, v56
	v_add_f32_e32 v57, 1.0, v57
	v_add_f32_e32 v58, 1.0, v58
	v_add_f32_e32 v59, 1.0, v59
	v_rcp_f32_e32 v56, v56
	v_rcp_f32_e32 v57, v57
	v_rcp_f32_e32 v58, v58
	v_rcp_f32_e32 v59, v59
	v_mul_f32_e32 v56, 0xbf1b4598, v56
	v_mul_f32_e32 v57, 0xbf1b4598, v57
	v_mul_f32_e32 v58, 0xbf1b4598, v58
	v_mul_f32_e32 v59, 0xbf1b4598, v59
	v_mul_f32_e32 v56, 0x3fb8aa3b, v56
	v_mul_f32_e32 v57, 0x3fb8aa3b, v57
	v_mul_f32_e32 v58, 0x3fb8aa3b, v58
	v_mul_f32_e32 v59, 0x3fb8aa3b, v59
	v_exp_f32_e32 v56, v56
	v_exp_f32_e32 v57, v57
	v_exp_f32_e32 v58, v58
	v_exp_f32_e32 v59, v59
	s_nop 0
	v_cvt_pk_f16_f32 v56, v56, v57
	v_cvt_pk_f16_f32 v57, v58, v59
	global_store_dwordx2 v137, v[56:57], s[18:19] offset:32
	v_add_f32_e32 v52, v52, v142
	v_add_f32_e32 v53, v53, v143
	v_add_f32_e32 v54, v54, v144
	v_add_f32_e32 v55, v55, v145
	v_mul_f32_e32 v52, 0xbfb8aa3b, v52
	v_mul_f32_e32 v53, 0xbfb8aa3b, v53
	v_mul_f32_e32 v54, 0xbfb8aa3b, v54
	v_mul_f32_e32 v55, 0xbfb8aa3b, v55
	v_exp_f32_e32 v52, v52
	v_exp_f32_e32 v53, v53
	v_exp_f32_e32 v54, v54
	v_exp_f32_e32 v55, v55
	v_add_f32_e32 v52, 1.0, v52
	v_add_f32_e32 v53, 1.0, v53
	v_add_f32_e32 v54, 1.0, v54
	v_add_f32_e32 v55, 1.0, v55
	v_rcp_f32_e32 v52, v52
	v_rcp_f32_e32 v53, v53
	v_rcp_f32_e32 v54, v54
	v_rcp_f32_e32 v55, v55
	v_mul_f32_e32 v52, 0xbf1b4598, v52
	v_mul_f32_e32 v53, 0xbf1b4598, v53
	v_mul_f32_e32 v54, 0xbf1b4598, v54
	v_mul_f32_e32 v55, 0xbf1b4598, v55
	v_mul_f32_e32 v52, 0x3fb8aa3b, v52
	v_mul_f32_e32 v53, 0x3fb8aa3b, v53
	v_mul_f32_e32 v54, 0x3fb8aa3b, v54
	v_mul_f32_e32 v55, 0x3fb8aa3b, v55
	v_exp_f32_e32 v52, v52
	v_exp_f32_e32 v53, v53
	v_exp_f32_e32 v54, v54
	v_exp_f32_e32 v55, v55
	s_nop 0
	v_cvt_pk_f16_f32 v52, v52, v53
	v_cvt_pk_f16_f32 v53, v54, v55
	global_store_dwordx2 v138, v[52:53], s[18:19]
	v_add_f32_e32 v48, v48, v146
	v_add_f32_e32 v49, v49, v147
	v_add_f32_e32 v50, v50, v148
	v_add_f32_e32 v51, v51, v149
	v_mul_f32_e32 v48, 0xbfb8aa3b, v48
	v_mul_f32_e32 v49, 0xbfb8aa3b, v49
	v_mul_f32_e32 v50, 0xbfb8aa3b, v50
	v_mul_f32_e32 v51, 0xbfb8aa3b, v51
	v_exp_f32_e32 v48, v48
	v_exp_f32_e32 v49, v49
	v_exp_f32_e32 v50, v50
	v_exp_f32_e32 v51, v51
	v_add_f32_e32 v48, 1.0, v48
	v_add_f32_e32 v49, 1.0, v49
	v_add_f32_e32 v50, 1.0, v50
	v_add_f32_e32 v51, 1.0, v51
	v_rcp_f32_e32 v48, v48
	v_rcp_f32_e32 v49, v49
	v_rcp_f32_e32 v50, v50
	v_rcp_f32_e32 v51, v51
	v_mul_f32_e32 v48, 0xbf1b4598, v48
	v_mul_f32_e32 v49, 0xbf1b4598, v49
	v_mul_f32_e32 v50, 0xbf1b4598, v50
	v_mul_f32_e32 v51, 0xbf1b4598, v51
	v_mul_f32_e32 v48, 0x3fb8aa3b, v48
	v_mul_f32_e32 v49, 0x3fb8aa3b, v49
	v_mul_f32_e32 v50, 0x3fb8aa3b, v50
	v_mul_f32_e32 v51, 0x3fb8aa3b, v51
	v_exp_f32_e32 v48, v48
	v_exp_f32_e32 v49, v49
	v_exp_f32_e32 v50, v50
	v_exp_f32_e32 v51, v51
	s_nop 0
	v_cvt_pk_f16_f32 v48, v48, v49
	v_cvt_pk_f16_f32 v49, v50, v51
	global_store_dwordx2 v138, v[48:49], s[18:19] offset:32
	v_add_f32_e32 v44, v44, v142
	v_add_f32_e32 v45, v45, v143
	v_add_f32_e32 v46, v46, v144
	v_add_f32_e32 v47, v47, v145
	v_mul_f32_e32 v44, 0xbfb8aa3b, v44
	v_mul_f32_e32 v45, 0xbfb8aa3b, v45
	v_mul_f32_e32 v46, 0xbfb8aa3b, v46
	v_mul_f32_e32 v47, 0xbfb8aa3b, v47
	v_exp_f32_e32 v44, v44
	v_exp_f32_e32 v45, v45
	v_exp_f32_e32 v46, v46
	v_exp_f32_e32 v47, v47
	v_add_f32_e32 v44, 1.0, v44
	v_add_f32_e32 v45, 1.0, v45
	v_add_f32_e32 v46, 1.0, v46
	v_add_f32_e32 v47, 1.0, v47
	v_rcp_f32_e32 v44, v44
	v_rcp_f32_e32 v45, v45
	v_rcp_f32_e32 v46, v46
	v_rcp_f32_e32 v47, v47
	v_mul_f32_e32 v44, 0xbf1b4598, v44
	v_mul_f32_e32 v45, 0xbf1b4598, v45
	v_mul_f32_e32 v46, 0xbf1b4598, v46
	v_mul_f32_e32 v47, 0xbf1b4598, v47
	v_mul_f32_e32 v44, 0x3fb8aa3b, v44
	v_mul_f32_e32 v45, 0x3fb8aa3b, v45
	v_mul_f32_e32 v46, 0x3fb8aa3b, v46
	v_mul_f32_e32 v47, 0x3fb8aa3b, v47
	v_exp_f32_e32 v44, v44
	v_exp_f32_e32 v45, v45
	v_exp_f32_e32 v46, v46
	v_exp_f32_e32 v47, v47
	s_nop 0
	v_cvt_pk_f16_f32 v44, v44, v45
	v_cvt_pk_f16_f32 v45, v46, v47
	global_store_dwordx2 v139, v[44:45], s[18:19]
	v_add_f32_e32 v40, v40, v146
	v_add_f32_e32 v41, v41, v147
	v_add_f32_e32 v42, v42, v148
	v_add_f32_e32 v43, v43, v149
	v_mul_f32_e32 v40, 0xbfb8aa3b, v40
	v_mul_f32_e32 v41, 0xbfb8aa3b, v41
	v_mul_f32_e32 v42, 0xbfb8aa3b, v42
	v_mul_f32_e32 v43, 0xbfb8aa3b, v43
	v_exp_f32_e32 v40, v40
	v_exp_f32_e32 v41, v41
	v_exp_f32_e32 v42, v42
	v_exp_f32_e32 v43, v43
	v_add_f32_e32 v40, 1.0, v40
	v_add_f32_e32 v41, 1.0, v41
	v_add_f32_e32 v42, 1.0, v42
	v_add_f32_e32 v43, 1.0, v43
	v_rcp_f32_e32 v40, v40
	v_rcp_f32_e32 v41, v41
	v_rcp_f32_e32 v42, v42
	v_rcp_f32_e32 v43, v43
	v_mul_f32_e32 v40, 0xbf1b4598, v40
	v_mul_f32_e32 v41, 0xbf1b4598, v41
	v_mul_f32_e32 v42, 0xbf1b4598, v42
	v_mul_f32_e32 v43, 0xbf1b4598, v43
	v_mul_f32_e32 v40, 0x3fb8aa3b, v40
	v_mul_f32_e32 v41, 0x3fb8aa3b, v41
	v_mul_f32_e32 v42, 0x3fb8aa3b, v42
	v_mul_f32_e32 v43, 0x3fb8aa3b, v43
	v_exp_f32_e32 v40, v40
	v_exp_f32_e32 v41, v41
	v_exp_f32_e32 v42, v42
	v_exp_f32_e32 v43, v43
	s_nop 0
	v_cvt_pk_f16_f32 v40, v40, v41
	v_cvt_pk_f16_f32 v41, v42, v43
	global_store_dwordx2 v139, v[40:41], s[18:19] offset:32
	v_add_f32_e32 v36, v36, v142
	v_add_f32_e32 v37, v37, v143
	v_add_f32_e32 v38, v38, v144
	v_add_f32_e32 v39, v39, v145
	v_mul_f32_e32 v36, 0xbfb8aa3b, v36
	v_mul_f32_e32 v37, 0xbfb8aa3b, v37
	v_mul_f32_e32 v38, 0xbfb8aa3b, v38
	v_mul_f32_e32 v39, 0xbfb8aa3b, v39
	v_exp_f32_e32 v36, v36
	v_exp_f32_e32 v37, v37
	v_exp_f32_e32 v38, v38
	v_exp_f32_e32 v39, v39
	v_add_f32_e32 v36, 1.0, v36
	v_add_f32_e32 v37, 1.0, v37
	v_add_f32_e32 v38, 1.0, v38
	v_add_f32_e32 v39, 1.0, v39
	v_rcp_f32_e32 v36, v36
	v_rcp_f32_e32 v37, v37
	v_rcp_f32_e32 v38, v38
	v_rcp_f32_e32 v39, v39
	v_mul_f32_e32 v36, 0xbf1b4598, v36
	v_mul_f32_e32 v37, 0xbf1b4598, v37
	v_mul_f32_e32 v38, 0xbf1b4598, v38
	v_mul_f32_e32 v39, 0xbf1b4598, v39
	v_mul_f32_e32 v36, 0x3fb8aa3b, v36
	v_mul_f32_e32 v37, 0x3fb8aa3b, v37
	v_mul_f32_e32 v38, 0x3fb8aa3b, v38
	v_mul_f32_e32 v39, 0x3fb8aa3b, v39
	v_exp_f32_e32 v36, v36
	v_exp_f32_e32 v37, v37
	v_exp_f32_e32 v38, v38
	v_exp_f32_e32 v39, v39
	s_nop 0
	v_cvt_pk_f16_f32 v36, v36, v37
	v_cvt_pk_f16_f32 v37, v38, v39
	global_store_dwordx2 v140, v[36:37], s[18:19]
	v_add_f32_e32 v32, v32, v146
	v_add_f32_e32 v33, v33, v147
	v_add_f32_e32 v34, v34, v148
	v_add_f32_e32 v35, v35, v149
	v_mul_f32_e32 v32, 0xbfb8aa3b, v32
	v_mul_f32_e32 v33, 0xbfb8aa3b, v33
	v_mul_f32_e32 v34, 0xbfb8aa3b, v34
	v_mul_f32_e32 v35, 0xbfb8aa3b, v35
	v_exp_f32_e32 v32, v32
	v_exp_f32_e32 v33, v33
	v_exp_f32_e32 v34, v34
	v_exp_f32_e32 v35, v35
	v_add_f32_e32 v32, 1.0, v32
	v_add_f32_e32 v33, 1.0, v33
	v_add_f32_e32 v34, 1.0, v34
	v_add_f32_e32 v35, 1.0, v35
	v_rcp_f32_e32 v32, v32
	v_rcp_f32_e32 v33, v33
	v_rcp_f32_e32 v34, v34
	v_rcp_f32_e32 v35, v35
	v_mul_f32_e32 v32, 0xbf1b4598, v32
	v_mul_f32_e32 v33, 0xbf1b4598, v33
	v_mul_f32_e32 v34, 0xbf1b4598, v34
	v_mul_f32_e32 v35, 0xbf1b4598, v35
	v_mul_f32_e32 v32, 0x3fb8aa3b, v32
	v_mul_f32_e32 v33, 0x3fb8aa3b, v33
	v_mul_f32_e32 v34, 0x3fb8aa3b, v34
	v_mul_f32_e32 v35, 0x3fb8aa3b, v35
	v_exp_f32_e32 v32, v32
	v_exp_f32_e32 v33, v33
	v_exp_f32_e32 v34, v34
	v_exp_f32_e32 v35, v35
	s_nop 0
	v_cvt_pk_f16_f32 v32, v32, v33
	v_cvt_pk_f16_f32 v33, v34, v35
	global_store_dwordx2 v140, v[32:33], s[18:19] offset:32
	v_add_f32_e32 v28, v28, v150
	v_add_f32_e32 v29, v29, v151
	v_add_f32_e32 v30, v30, v152
	v_add_f32_e32 v31, v31, v153
	v_mul_f32_e32 v28, 0xbfb8aa3b, v28
	v_mul_f32_e32 v29, 0xbfb8aa3b, v29
	v_mul_f32_e32 v30, 0xbfb8aa3b, v30
	v_mul_f32_e32 v31, 0xbfb8aa3b, v31
	v_exp_f32_e32 v28, v28
	v_exp_f32_e32 v29, v29
	v_exp_f32_e32 v30, v30
	v_exp_f32_e32 v31, v31
	v_add_f32_e32 v28, 1.0, v28
	v_add_f32_e32 v29, 1.0, v29
	v_add_f32_e32 v30, 1.0, v30
	v_add_f32_e32 v31, 1.0, v31
	v_rcp_f32_e32 v28, v28
	v_rcp_f32_e32 v29, v29
	v_rcp_f32_e32 v30, v30
	v_rcp_f32_e32 v31, v31
	v_mul_f32_e32 v28, 0xbf1b4598, v28
	v_mul_f32_e32 v29, 0xbf1b4598, v29
	v_mul_f32_e32 v30, 0xbf1b4598, v30
	v_mul_f32_e32 v31, 0xbf1b4598, v31
	v_mul_f32_e32 v28, 0x3fb8aa3b, v28
	v_mul_f32_e32 v29, 0x3fb8aa3b, v29
	v_mul_f32_e32 v30, 0x3fb8aa3b, v30
	v_mul_f32_e32 v31, 0x3fb8aa3b, v31
	v_exp_f32_e32 v28, v28
	v_exp_f32_e32 v29, v29
	v_exp_f32_e32 v30, v30
	v_exp_f32_e32 v31, v31
	s_nop 0
	v_cvt_pk_f16_f32 v28, v28, v29
	v_cvt_pk_f16_f32 v29, v30, v31
	global_store_dwordx2 v137, v[28:29], s[18:19] offset:256
	v_add_f32_e32 v24, v24, v154
	v_add_f32_e32 v25, v25, v155
	v_add_f32_e32 v26, v26, v156
	v_add_f32_e32 v27, v27, v157
	v_mul_f32_e32 v24, 0xbfb8aa3b, v24
	v_mul_f32_e32 v25, 0xbfb8aa3b, v25
	v_mul_f32_e32 v26, 0xbfb8aa3b, v26
	v_mul_f32_e32 v27, 0xbfb8aa3b, v27
	v_exp_f32_e32 v24, v24
	v_exp_f32_e32 v25, v25
	v_exp_f32_e32 v26, v26
	v_exp_f32_e32 v27, v27
	v_add_f32_e32 v24, 1.0, v24
	v_add_f32_e32 v25, 1.0, v25
	v_add_f32_e32 v26, 1.0, v26
	v_add_f32_e32 v27, 1.0, v27
	v_rcp_f32_e32 v24, v24
	v_rcp_f32_e32 v25, v25
	v_rcp_f32_e32 v26, v26
	v_rcp_f32_e32 v27, v27
	v_mul_f32_e32 v24, 0xbf1b4598, v24
	v_mul_f32_e32 v25, 0xbf1b4598, v25
	v_mul_f32_e32 v26, 0xbf1b4598, v26
	v_mul_f32_e32 v27, 0xbf1b4598, v27
	v_mul_f32_e32 v24, 0x3fb8aa3b, v24
	v_mul_f32_e32 v25, 0x3fb8aa3b, v25
	v_mul_f32_e32 v26, 0x3fb8aa3b, v26
	v_mul_f32_e32 v27, 0x3fb8aa3b, v27
	v_exp_f32_e32 v24, v24
	v_exp_f32_e32 v25, v25
	v_exp_f32_e32 v26, v26
	v_exp_f32_e32 v27, v27
	s_nop 0
	v_cvt_pk_f16_f32 v24, v24, v25
	v_cvt_pk_f16_f32 v25, v26, v27
	global_store_dwordx2 v137, v[24:25], s[18:19] offset:288
	v_add_f32_e32 v20, v20, v150
	v_add_f32_e32 v21, v21, v151
	v_add_f32_e32 v22, v22, v152
	v_add_f32_e32 v23, v23, v153
	v_mul_f32_e32 v20, 0xbfb8aa3b, v20
	v_mul_f32_e32 v21, 0xbfb8aa3b, v21
	v_mul_f32_e32 v22, 0xbfb8aa3b, v22
	v_mul_f32_e32 v23, 0xbfb8aa3b, v23
	v_exp_f32_e32 v20, v20
	v_exp_f32_e32 v21, v21
	v_exp_f32_e32 v22, v22
	v_exp_f32_e32 v23, v23
	v_add_f32_e32 v20, 1.0, v20
	v_add_f32_e32 v21, 1.0, v21
	v_add_f32_e32 v22, 1.0, v22
	v_add_f32_e32 v23, 1.0, v23
	v_rcp_f32_e32 v20, v20
	v_rcp_f32_e32 v21, v21
	v_rcp_f32_e32 v22, v22
	v_rcp_f32_e32 v23, v23
	v_mul_f32_e32 v20, 0xbf1b4598, v20
	v_mul_f32_e32 v21, 0xbf1b4598, v21
	v_mul_f32_e32 v22, 0xbf1b4598, v22
	v_mul_f32_e32 v23, 0xbf1b4598, v23
	v_mul_f32_e32 v20, 0x3fb8aa3b, v20
	v_mul_f32_e32 v21, 0x3fb8aa3b, v21
	v_mul_f32_e32 v22, 0x3fb8aa3b, v22
	v_mul_f32_e32 v23, 0x3fb8aa3b, v23
	v_exp_f32_e32 v20, v20
	v_exp_f32_e32 v21, v21
	v_exp_f32_e32 v22, v22
	v_exp_f32_e32 v23, v23
	s_nop 0
	v_cvt_pk_f16_f32 v20, v20, v21
	v_cvt_pk_f16_f32 v21, v22, v23
	global_store_dwordx2 v138, v[20:21], s[18:19] offset:256
	v_add_f32_e32 v16, v16, v154
	v_add_f32_e32 v17, v17, v155
	v_add_f32_e32 v18, v18, v156
	v_add_f32_e32 v19, v19, v157
	v_mul_f32_e32 v16, 0xbfb8aa3b, v16
	v_mul_f32_e32 v17, 0xbfb8aa3b, v17
	v_mul_f32_e32 v18, 0xbfb8aa3b, v18
	v_mul_f32_e32 v19, 0xbfb8aa3b, v19
	v_exp_f32_e32 v16, v16
	v_exp_f32_e32 v17, v17
	v_exp_f32_e32 v18, v18
	v_exp_f32_e32 v19, v19
	v_add_f32_e32 v16, 1.0, v16
	v_add_f32_e32 v17, 1.0, v17
	v_add_f32_e32 v18, 1.0, v18
	v_add_f32_e32 v19, 1.0, v19
	v_rcp_f32_e32 v16, v16
	v_rcp_f32_e32 v17, v17
	v_rcp_f32_e32 v18, v18
	v_rcp_f32_e32 v19, v19
	v_mul_f32_e32 v16, 0xbf1b4598, v16
	v_mul_f32_e32 v17, 0xbf1b4598, v17
	v_mul_f32_e32 v18, 0xbf1b4598, v18
	v_mul_f32_e32 v19, 0xbf1b4598, v19
	v_mul_f32_e32 v16, 0x3fb8aa3b, v16
	v_mul_f32_e32 v17, 0x3fb8aa3b, v17
	v_mul_f32_e32 v18, 0x3fb8aa3b, v18
	v_mul_f32_e32 v19, 0x3fb8aa3b, v19
	v_exp_f32_e32 v16, v16
	v_exp_f32_e32 v17, v17
	v_exp_f32_e32 v18, v18
	v_exp_f32_e32 v19, v19
	s_nop 0
	v_cvt_pk_f16_f32 v16, v16, v17
	v_cvt_pk_f16_f32 v17, v18, v19
	global_store_dwordx2 v138, v[16:17], s[18:19] offset:288
	v_add_f32_e32 v12, v12, v150
	v_add_f32_e32 v13, v13, v151
	v_add_f32_e32 v14, v14, v152
	v_add_f32_e32 v15, v15, v153
	v_mul_f32_e32 v12, 0xbfb8aa3b, v12
	v_mul_f32_e32 v13, 0xbfb8aa3b, v13
	v_mul_f32_e32 v14, 0xbfb8aa3b, v14
	v_mul_f32_e32 v15, 0xbfb8aa3b, v15
	v_exp_f32_e32 v12, v12
	v_exp_f32_e32 v13, v13
	v_exp_f32_e32 v14, v14
	v_exp_f32_e32 v15, v15
	v_add_f32_e32 v12, 1.0, v12
	v_add_f32_e32 v13, 1.0, v13
	v_add_f32_e32 v14, 1.0, v14
	v_add_f32_e32 v15, 1.0, v15
	v_rcp_f32_e32 v12, v12
	v_rcp_f32_e32 v13, v13
	v_rcp_f32_e32 v14, v14
	v_rcp_f32_e32 v15, v15
	v_mul_f32_e32 v12, 0xbf1b4598, v12
	v_mul_f32_e32 v13, 0xbf1b4598, v13
	v_mul_f32_e32 v14, 0xbf1b4598, v14
	v_mul_f32_e32 v15, 0xbf1b4598, v15
	v_mul_f32_e32 v12, 0x3fb8aa3b, v12
	v_mul_f32_e32 v13, 0x3fb8aa3b, v13
	v_mul_f32_e32 v14, 0x3fb8aa3b, v14
	v_mul_f32_e32 v15, 0x3fb8aa3b, v15
	v_exp_f32_e32 v12, v12
	v_exp_f32_e32 v13, v13
	v_exp_f32_e32 v14, v14
	v_exp_f32_e32 v15, v15
	s_nop 0
	v_cvt_pk_f16_f32 v12, v12, v13
	v_cvt_pk_f16_f32 v13, v14, v15
	global_store_dwordx2 v139, v[12:13], s[18:19] offset:256
	v_add_f32_e32 v8, v8, v154
	v_add_f32_e32 v9, v9, v155
	v_add_f32_e32 v10, v10, v156
	v_add_f32_e32 v11, v11, v157
	v_mul_f32_e32 v8, 0xbfb8aa3b, v8
	v_mul_f32_e32 v9, 0xbfb8aa3b, v9
	v_mul_f32_e32 v10, 0xbfb8aa3b, v10
	v_mul_f32_e32 v11, 0xbfb8aa3b, v11
	v_exp_f32_e32 v8, v8
	v_exp_f32_e32 v9, v9
	v_exp_f32_e32 v10, v10
	v_exp_f32_e32 v11, v11
	v_add_f32_e32 v8, 1.0, v8
	v_add_f32_e32 v9, 1.0, v9
	v_add_f32_e32 v10, 1.0, v10
	v_add_f32_e32 v11, 1.0, v11
	v_rcp_f32_e32 v8, v8
	v_rcp_f32_e32 v9, v9
	v_rcp_f32_e32 v10, v10
	v_rcp_f32_e32 v11, v11
	v_mul_f32_e32 v8, 0xbf1b4598, v8
	v_mul_f32_e32 v9, 0xbf1b4598, v9
	v_mul_f32_e32 v10, 0xbf1b4598, v10
	v_mul_f32_e32 v11, 0xbf1b4598, v11
	v_mul_f32_e32 v8, 0x3fb8aa3b, v8
	v_mul_f32_e32 v9, 0x3fb8aa3b, v9
	v_mul_f32_e32 v10, 0x3fb8aa3b, v10
	v_mul_f32_e32 v11, 0x3fb8aa3b, v11
	v_exp_f32_e32 v8, v8
	v_exp_f32_e32 v9, v9
	v_exp_f32_e32 v10, v10
	v_exp_f32_e32 v11, v11
	s_nop 0
	v_cvt_pk_f16_f32 v8, v8, v9
	v_cvt_pk_f16_f32 v9, v10, v11
	global_store_dwordx2 v139, v[8:9], s[18:19] offset:288
	v_add_f32_e32 v4, v4, v150
	v_add_f32_e32 v5, v5, v151
	v_add_f32_e32 v6, v6, v152
	v_add_f32_e32 v7, v7, v153
	v_mul_f32_e32 v4, 0xbfb8aa3b, v4
	v_mul_f32_e32 v5, 0xbfb8aa3b, v5
	v_mul_f32_e32 v6, 0xbfb8aa3b, v6
	v_mul_f32_e32 v7, 0xbfb8aa3b, v7
	v_exp_f32_e32 v4, v4
	v_exp_f32_e32 v5, v5
	v_exp_f32_e32 v6, v6
	v_exp_f32_e32 v7, v7
	v_add_f32_e32 v4, 1.0, v4
	v_add_f32_e32 v5, 1.0, v5
	v_add_f32_e32 v6, 1.0, v6
	v_add_f32_e32 v7, 1.0, v7
	v_rcp_f32_e32 v4, v4
	v_rcp_f32_e32 v5, v5
	v_rcp_f32_e32 v6, v6
	v_rcp_f32_e32 v7, v7
	v_mul_f32_e32 v4, 0xbf1b4598, v4
	v_mul_f32_e32 v5, 0xbf1b4598, v5
	v_mul_f32_e32 v6, 0xbf1b4598, v6
	v_mul_f32_e32 v7, 0xbf1b4598, v7
	v_mul_f32_e32 v4, 0x3fb8aa3b, v4
	v_mul_f32_e32 v5, 0x3fb8aa3b, v5
	v_mul_f32_e32 v6, 0x3fb8aa3b, v6
	v_mul_f32_e32 v7, 0x3fb8aa3b, v7
	v_exp_f32_e32 v4, v4
	v_exp_f32_e32 v5, v5
	v_exp_f32_e32 v6, v6
	v_exp_f32_e32 v7, v7
	s_nop 0
	v_cvt_pk_f16_f32 v4, v4, v5
	v_cvt_pk_f16_f32 v5, v6, v7
	global_store_dwordx2 v140, v[4:5], s[18:19] offset:256
	v_add_f32_e32 v0, v0, v154
	v_add_f32_e32 v1, v1, v155
	v_add_f32_e32 v2, v2, v156
	v_add_f32_e32 v3, v3, v157
	v_mul_f32_e32 v0, 0xbfb8aa3b, v0
	v_mul_f32_e32 v1, 0xbfb8aa3b, v1
	v_mul_f32_e32 v2, 0xbfb8aa3b, v2
	v_mul_f32_e32 v3, 0xbfb8aa3b, v3
	v_exp_f32_e32 v0, v0
	v_exp_f32_e32 v1, v1
	v_exp_f32_e32 v2, v2
	v_exp_f32_e32 v3, v3
	v_add_f32_e32 v0, 1.0, v0
	v_add_f32_e32 v1, 1.0, v1
	v_add_f32_e32 v2, 1.0, v2
	v_add_f32_e32 v3, 1.0, v3
	v_rcp_f32_e32 v0, v0
	v_rcp_f32_e32 v1, v1
	v_rcp_f32_e32 v2, v2
	v_rcp_f32_e32 v3, v3
	v_mul_f32_e32 v0, 0xbf1b4598, v0
	v_mul_f32_e32 v1, 0xbf1b4598, v1
	v_mul_f32_e32 v2, 0xbf1b4598, v2
	v_mul_f32_e32 v3, 0xbf1b4598, v3
	v_mul_f32_e32 v0, 0x3fb8aa3b, v0
	v_mul_f32_e32 v1, 0x3fb8aa3b, v1
	v_mul_f32_e32 v2, 0x3fb8aa3b, v2
	v_mul_f32_e32 v3, 0x3fb8aa3b, v3
	v_exp_f32_e32 v0, v0
	v_exp_f32_e32 v1, v1
	v_exp_f32_e32 v2, v2
	v_exp_f32_e32 v3, v3
	s_nop 0
	v_cvt_pk_f16_f32 v0, v0, v1
	v_cvt_pk_f16_f32 v1, v2, v3
	global_store_dwordx2 v140, v[0:1], s[18:19] offset:288
	s_branch .Llora_done
.Llora_a:
	global_load_dwordx4 v[142:145], v133, s[14:15] offset:-2048
	global_load_dwordx4 v[146:149], v133, s[14:15] offset:-1984
	global_load_dwordx4 v[150:153], v133, s[14:15] offset:-1536
	global_load_dwordx4 v[154:157], v133, s[14:15] offset:-1472
	s_waitcnt vmcnt(0)
	v_add_f32_e32 v124, v124, v142
	v_add_f32_e32 v125, v125, v143
	v_add_f32_e32 v126, v126, v144
	v_add_f32_e32 v127, v127, v145
	v_mul_f32_e32 v124, 0xbfb8aa3b, v124
	v_mul_f32_e32 v125, 0xbfb8aa3b, v125
	v_mul_f32_e32 v126, 0xbfb8aa3b, v126
	v_mul_f32_e32 v127, 0xbfb8aa3b, v127
	v_exp_f32_e32 v124, v124
	v_exp_f32_e32 v125, v125
	v_exp_f32_e32 v126, v126
	v_exp_f32_e32 v127, v127
	v_add_f32_e32 v124, 1.0, v124
	v_add_f32_e32 v125, 1.0, v125
	v_add_f32_e32 v126, 1.0, v126
	v_add_f32_e32 v127, 1.0, v127
	v_rcp_f32_e32 v124, v124
	v_rcp_f32_e32 v125, v125
	v_rcp_f32_e32 v126, v126
	v_rcp_f32_e32 v127, v127
	s_nop 0
	v_cvt_pk_f16_f32 v124, v124, v125
	v_cvt_pk_f16_f32 v125, v126, v127
	global_store_dwordx2 v131, v[124:125], s[4:5] offset:-1024
	v_add_f32_e32 v120, v120, v146
	v_add_f32_e32 v121, v121, v147
	v_add_f32_e32 v122, v122, v148
	v_add_f32_e32 v123, v123, v149
	v_mul_f32_e32 v120, 0xbfb8aa3b, v120
	v_mul_f32_e32 v121, 0xbfb8aa3b, v121
	v_mul_f32_e32 v122, 0xbfb8aa3b, v122
	v_mul_f32_e32 v123, 0xbfb8aa3b, v123
	v_exp_f32_e32 v120, v120
	v_exp_f32_e32 v121, v121
	v_exp_f32_e32 v122, v122
	v_exp_f32_e32 v123, v123
	v_add_f32_e32 v120, 1.0, v120
	v_add_f32_e32 v121, 1.0, v121
	v_add_f32_e32 v122, 1.0, v122
	v_add_f32_e32 v123, 1.0, v123
	v_rcp_f32_e32 v120, v120
	v_rcp_f32_e32 v121, v121
	v_rcp_f32_e32 v122, v122
	v_rcp_f32_e32 v123, v123
	s_nop 0
	v_cvt_pk_f16_f32 v120, v120, v121
	v_cvt_pk_f16_f32 v121, v122, v123
	global_store_dwordx2 v131, v[120:121], s[4:5] offset:-992
	v_add_f32_e32 v116, v116, v142
	v_add_f32_e32 v117, v117, v143
	v_add_f32_e32 v118, v118, v144
	v_add_f32_e32 v119, v119, v145
	v_mul_f32_e32 v116, 0xbfb8aa3b, v116
	v_mul_f32_e32 v117, 0xbfb8aa3b, v117
	v_mul_f32_e32 v118, 0xbfb8aa3b, v118
	v_mul_f32_e32 v119, 0xbfb8aa3b, v119
	v_exp_f32_e32 v116, v116
	v_exp_f32_e32 v117, v117
	v_exp_f32_e32 v118, v118
	v_exp_f32_e32 v119, v119
	v_add_f32_e32 v116, 1.0, v116
	v_add_f32_e32 v117, 1.0, v117
	v_add_f32_e32 v118, 1.0, v118
	v_add_f32_e32 v119, 1.0, v119
	v_rcp_f32_e32 v116, v116
	v_rcp_f32_e32 v117, v117
	v_rcp_f32_e32 v118, v118
	v_rcp_f32_e32 v119, v119
	s_nop 0
	v_cvt_pk_f16_f32 v116, v116, v117
	v_cvt_pk_f16_f32 v117, v118, v119
	global_store_dwordx2 v134, v[116:117], s[4:5] offset:-1024
	v_add_f32_e32 v112, v112, v146
	v_add_f32_e32 v113, v113, v147
	v_add_f32_e32 v114, v114, v148
	v_add_f32_e32 v115, v115, v149
	v_mul_f32_e32 v112, 0xbfb8aa3b, v112
	v_mul_f32_e32 v113, 0xbfb8aa3b, v113
	v_mul_f32_e32 v114, 0xbfb8aa3b, v114
	v_mul_f32_e32 v115, 0xbfb8aa3b, v115
	v_exp_f32_e32 v112, v112
	v_exp_f32_e32 v113, v113
	v_exp_f32_e32 v114, v114
	v_exp_f32_e32 v115, v115
	v_add_f32_e32 v112, 1.0, v112
	v_add_f32_e32 v113, 1.0, v113
	v_add_f32_e32 v114, 1.0, v114
	v_add_f32_e32 v115, 1.0, v115
	v_rcp_f32_e32 v112, v112
	v_rcp_f32_e32 v113, v113
	v_rcp_f32_e32 v114, v114
	v_rcp_f32_e32 v115, v115
	s_nop 0
	v_cvt_pk_f16_f32 v112, v112, v113
	v_cvt_pk_f16_f32 v113, v114, v115
	global_store_dwordx2 v134, v[112:113], s[4:5] offset:-992
	v_add_f32_e32 v108, v108, v142
	v_add_f32_e32 v109, v109, v143
	v_add_f32_e32 v110, v110, v144
	v_add_f32_e32 v111, v111, v145
	v_mul_f32_e32 v108, 0xbfb8aa3b, v108
	v_mul_f32_e32 v109, 0xbfb8aa3b, v109
	v_mul_f32_e32 v110, 0xbfb8aa3b, v110
	v_mul_f32_e32 v111, 0xbfb8aa3b, v111
	v_exp_f32_e32 v108, v108
	v_exp_f32_e32 v109, v109
	v_exp_f32_e32 v110, v110
	v_exp_f32_e32 v111, v111
	v_add_f32_e32 v108, 1.0, v108
	v_add_f32_e32 v109, 1.0, v109
	v_add_f32_e32 v110, 1.0, v110
	v_add_f32_e32 v111, 1.0, v111
	v_rcp_f32_e32 v108, v108
	v_rcp_f32_e32 v109, v109
	v_rcp_f32_e32 v110, v110
	v_rcp_f32_e32 v111, v111
	s_nop 0
	v_cvt_pk_f16_f32 v108, v108, v109
	v_cvt_pk_f16_f32 v109, v110, v111
	global_store_dwordx2 v135, v[108:109], s[4:5] offset:-1024
	v_add_f32_e32 v104, v104, v146
	v_add_f32_e32 v105, v105, v147
	v_add_f32_e32 v106, v106, v148
	v_add_f32_e32 v107, v107, v149
	v_mul_f32_e32 v104, 0xbfb8aa3b, v104
	v_mul_f32_e32 v105, 0xbfb8aa3b, v105
	v_mul_f32_e32 v106, 0xbfb8aa3b, v106
	v_mul_f32_e32 v107, 0xbfb8aa3b, v107
	v_exp_f32_e32 v104, v104
	v_exp_f32_e32 v105, v105
	v_exp_f32_e32 v106, v106
	v_exp_f32_e32 v107, v107
	v_add_f32_e32 v104, 1.0, v104
	v_add_f32_e32 v105, 1.0, v105
	v_add_f32_e32 v106, 1.0, v106
	v_add_f32_e32 v107, 1.0, v107
	v_rcp_f32_e32 v104, v104
	v_rcp_f32_e32 v105, v105
	v_rcp_f32_e32 v106, v106
	v_rcp_f32_e32 v107, v107
	s_nop 0
	v_cvt_pk_f16_f32 v104, v104, v105
	v_cvt_pk_f16_f32 v105, v106, v107
	global_store_dwordx2 v135, v[104:105], s[4:5] offset:-992
	v_add_f32_e32 v100, v100, v142
	v_add_f32_e32 v101, v101, v143
	v_add_f32_e32 v102, v102, v144
	v_add_f32_e32 v103, v103, v145
	v_mul_f32_e32 v100, 0xbfb8aa3b, v100
	v_mul_f32_e32 v101, 0xbfb8aa3b, v101
	v_mul_f32_e32 v102, 0xbfb8aa3b, v102
	v_mul_f32_e32 v103, 0xbfb8aa3b, v103
	v_exp_f32_e32 v100, v100
	v_exp_f32_e32 v101, v101
	v_exp_f32_e32 v102, v102
	v_exp_f32_e32 v103, v103
	v_add_f32_e32 v100, 1.0, v100
	v_add_f32_e32 v101, 1.0, v101
	v_add_f32_e32 v102, 1.0, v102
	v_add_f32_e32 v103, 1.0, v103
	v_rcp_f32_e32 v100, v100
	v_rcp_f32_e32 v101, v101
	v_rcp_f32_e32 v102, v102
	v_rcp_f32_e32 v103, v103
	s_nop 0
	v_cvt_pk_f16_f32 v100, v100, v101
	v_cvt_pk_f16_f32 v101, v102, v103
	global_store_dwordx2 v136, v[100:101], s[4:5] offset:-1024
	v_add_f32_e32 v96, v96, v146
	v_add_f32_e32 v97, v97, v147
	v_add_f32_e32 v98, v98, v148
	v_add_f32_e32 v99, v99, v149
	v_mul_f32_e32 v96, 0xbfb8aa3b, v96
	v_mul_f32_e32 v97, 0xbfb8aa3b, v97
	v_mul_f32_e32 v98, 0xbfb8aa3b, v98
	v_mul_f32_e32 v99, 0xbfb8aa3b, v99
	v_exp_f32_e32 v96, v96
	v_exp_f32_e32 v97, v97
	v_exp_f32_e32 v98, v98
	v_exp_f32_e32 v99, v99
	v_add_f32_e32 v96, 1.0, v96
	v_add_f32_e32 v97, 1.0, v97
	v_add_f32_e32 v98, 1.0, v98
	v_add_f32_e32 v99, 1.0, v99
	v_rcp_f32_e32 v96, v96
	v_rcp_f32_e32 v97, v97
	v_rcp_f32_e32 v98, v98
	v_rcp_f32_e32 v99, v99
	s_nop 0
	v_cvt_pk_f16_f32 v96, v96, v97
	v_cvt_pk_f16_f32 v97, v98, v99
	global_store_dwordx2 v136, v[96:97], s[4:5] offset:-992
	v_add_f32_e32 v92, v92, v150
	v_add_f32_e32 v93, v93, v151
	v_add_f32_e32 v94, v94, v152
	v_add_f32_e32 v95, v95, v153
	v_mul_f32_e32 v92, 0xbfb8aa3b, v92
	v_mul_f32_e32 v93, 0xbfb8aa3b, v93
	v_mul_f32_e32 v94, 0xbfb8aa3b, v94
	v_mul_f32_e32 v95, 0xbfb8aa3b, v95
	v_exp_f32_e32 v92, v92
	v_exp_f32_e32 v93, v93
	v_exp_f32_e32 v94, v94
	v_exp_f32_e32 v95, v95
	v_add_f32_e32 v92, 1.0, v92
	v_add_f32_e32 v93, 1.0, v93
	v_add_f32_e32 v94, 1.0, v94
	v_add_f32_e32 v95, 1.0, v95
	v_rcp_f32_e32 v92, v92
	v_rcp_f32_e32 v93, v93
	v_rcp_f32_e32 v94, v94
	v_rcp_f32_e32 v95, v95
	s_nop 0
	v_cvt_pk_f16_f32 v92, v92, v93
	v_cvt_pk_f16_f32 v93, v94, v95
	global_store_dwordx2 v131, v[92:93], s[4:5] offset:-768
	v_add_f32_e32 v88, v88, v154
	v_add_f32_e32 v89, v89, v155
	v_add_f32_e32 v90, v90, v156
	v_add_f32_e32 v91, v91, v157
	v_mul_f32_e32 v88, 0xbfb8aa3b, v88
	v_mul_f32_e32 v89, 0xbfb8aa3b, v89
	v_mul_f32_e32 v90, 0xbfb8aa3b, v90
	v_mul_f32_e32 v91, 0xbfb8aa3b, v91
	v_exp_f32_e32 v88, v88
	v_exp_f32_e32 v89, v89
	v_exp_f32_e32 v90, v90
	v_exp_f32_e32 v91, v91
	v_add_f32_e32 v88, 1.0, v88
	v_add_f32_e32 v89, 1.0, v89
	v_add_f32_e32 v90, 1.0, v90
	v_add_f32_e32 v91, 1.0, v91
	v_rcp_f32_e32 v88, v88
	v_rcp_f32_e32 v89, v89
	v_rcp_f32_e32 v90, v90
	v_rcp_f32_e32 v91, v91
	s_nop 0
	v_cvt_pk_f16_f32 v88, v88, v89
	v_cvt_pk_f16_f32 v89, v90, v91
	global_store_dwordx2 v131, v[88:89], s[4:5] offset:-736
	v_add_f32_e32 v84, v84, v150
	v_add_f32_e32 v85, v85, v151
	v_add_f32_e32 v86, v86, v152
	v_add_f32_e32 v87, v87, v153
	v_mul_f32_e32 v84, 0xbfb8aa3b, v84
	v_mul_f32_e32 v85, 0xbfb8aa3b, v85
	v_mul_f32_e32 v86, 0xbfb8aa3b, v86
	v_mul_f32_e32 v87, 0xbfb8aa3b, v87
	v_exp_f32_e32 v84, v84
	v_exp_f32_e32 v85, v85
	v_exp_f32_e32 v86, v86
	v_exp_f32_e32 v87, v87
	v_add_f32_e32 v84, 1.0, v84
	v_add_f32_e32 v85, 1.0, v85
	v_add_f32_e32 v86, 1.0, v86
	v_add_f32_e32 v87, 1.0, v87
	v_rcp_f32_e32 v84, v84
	v_rcp_f32_e32 v85, v85
	v_rcp_f32_e32 v86, v86
	v_rcp_f32_e32 v87, v87
	s_nop 0
	v_cvt_pk_f16_f32 v84, v84, v85
	v_cvt_pk_f16_f32 v85, v86, v87
	global_store_dwordx2 v134, v[84:85], s[4:5] offset:-768
	v_add_f32_e32 v80, v80, v154
	v_add_f32_e32 v81, v81, v155
	v_add_f32_e32 v82, v82, v156
	v_add_f32_e32 v83, v83, v157
	v_mul_f32_e32 v80, 0xbfb8aa3b, v80
	v_mul_f32_e32 v81, 0xbfb8aa3b, v81
	v_mul_f32_e32 v82, 0xbfb8aa3b, v82
	v_mul_f32_e32 v83, 0xbfb8aa3b, v83
	v_exp_f32_e32 v80, v80
	v_exp_f32_e32 v81, v81
	v_exp_f32_e32 v82, v82
	v_exp_f32_e32 v83, v83
	v_add_f32_e32 v80, 1.0, v80
	v_add_f32_e32 v81, 1.0, v81
	v_add_f32_e32 v82, 1.0, v82
	v_add_f32_e32 v83, 1.0, v83
	v_rcp_f32_e32 v80, v80
	v_rcp_f32_e32 v81, v81
	v_rcp_f32_e32 v82, v82
	v_rcp_f32_e32 v83, v83
	s_nop 0
	v_cvt_pk_f16_f32 v80, v80, v81
	v_cvt_pk_f16_f32 v81, v82, v83
	global_store_dwordx2 v134, v[80:81], s[4:5] offset:-736
	v_add_f32_e32 v76, v76, v150
	v_add_f32_e32 v77, v77, v151
	v_add_f32_e32 v78, v78, v152
	v_add_f32_e32 v79, v79, v153
	v_mul_f32_e32 v76, 0xbfb8aa3b, v76
	v_mul_f32_e32 v77, 0xbfb8aa3b, v77
	v_mul_f32_e32 v78, 0xbfb8aa3b, v78
	v_mul_f32_e32 v79, 0xbfb8aa3b, v79
	v_exp_f32_e32 v76, v76
	v_exp_f32_e32 v77, v77
	v_exp_f32_e32 v78, v78
	v_exp_f32_e32 v79, v79
	v_add_f32_e32 v76, 1.0, v76
	v_add_f32_e32 v77, 1.0, v77
	v_add_f32_e32 v78, 1.0, v78
	v_add_f32_e32 v79, 1.0, v79
	v_rcp_f32_e32 v76, v76
	v_rcp_f32_e32 v77, v77
	v_rcp_f32_e32 v78, v78
	v_rcp_f32_e32 v79, v79
	s_nop 0
	v_cvt_pk_f16_f32 v76, v76, v77
	v_cvt_pk_f16_f32 v77, v78, v79
	global_store_dwordx2 v135, v[76:77], s[4:5] offset:-768
	v_add_f32_e32 v72, v72, v154
	v_add_f32_e32 v73, v73, v155
	v_add_f32_e32 v74, v74, v156
	v_add_f32_e32 v75, v75, v157
	v_mul_f32_e32 v72, 0xbfb8aa3b, v72
	v_mul_f32_e32 v73, 0xbfb8aa3b, v73
	v_mul_f32_e32 v74, 0xbfb8aa3b, v74
	v_mul_f32_e32 v75, 0xbfb8aa3b, v75
	v_exp_f32_e32 v72, v72
	v_exp_f32_e32 v73, v73
	v_exp_f32_e32 v74, v74
	v_exp_f32_e32 v75, v75
	v_add_f32_e32 v72, 1.0, v72
	v_add_f32_e32 v73, 1.0, v73
	v_add_f32_e32 v74, 1.0, v74
	v_add_f32_e32 v75, 1.0, v75
	v_rcp_f32_e32 v72, v72
	v_rcp_f32_e32 v73, v73
	v_rcp_f32_e32 v74, v74
	v_rcp_f32_e32 v75, v75
	s_nop 0
	v_cvt_pk_f16_f32 v72, v72, v73
	v_cvt_pk_f16_f32 v73, v74, v75
	global_store_dwordx2 v135, v[72:73], s[4:5] offset:-736
	v_add_f32_e32 v68, v68, v150
	v_add_f32_e32 v69, v69, v151
	v_add_f32_e32 v70, v70, v152
	v_add_f32_e32 v71, v71, v153
	v_mul_f32_e32 v68, 0xbfb8aa3b, v68
	v_mul_f32_e32 v69, 0xbfb8aa3b, v69
	v_mul_f32_e32 v70, 0xbfb8aa3b, v70
	v_mul_f32_e32 v71, 0xbfb8aa3b, v71
	v_exp_f32_e32 v68, v68
	v_exp_f32_e32 v69, v69
	v_exp_f32_e32 v70, v70
	v_exp_f32_e32 v71, v71
	v_add_f32_e32 v68, 1.0, v68
	v_add_f32_e32 v69, 1.0, v69
	v_add_f32_e32 v70, 1.0, v70
	v_add_f32_e32 v71, 1.0, v71
	v_rcp_f32_e32 v68, v68
	v_rcp_f32_e32 v69, v69
	v_rcp_f32_e32 v70, v70
	v_rcp_f32_e32 v71, v71
	s_nop 0
	v_cvt_pk_f16_f32 v68, v68, v69
	v_cvt_pk_f16_f32 v69, v70, v71
	global_store_dwordx2 v136, v[68:69], s[4:5] offset:-768
	v_add_f32_e32 v64, v64, v154
	v_add_f32_e32 v65, v65, v155
	v_add_f32_e32 v66, v66, v156
	v_add_f32_e32 v67, v67, v157
	v_mul_f32_e32 v64, 0xbfb8aa3b, v64
	v_mul_f32_e32 v65, 0xbfb8aa3b, v65
	v_mul_f32_e32 v66, 0xbfb8aa3b, v66
	v_mul_f32_e32 v67, 0xbfb8aa3b, v67
	v_exp_f32_e32 v64, v64
	v_exp_f32_e32 v65, v65
	v_exp_f32_e32 v66, v66
	v_exp_f32_e32 v67, v67
	v_add_f32_e32 v64, 1.0, v64
	v_add_f32_e32 v65, 1.0, v65
	v_add_f32_e32 v66, 1.0, v66
	v_add_f32_e32 v67, 1.0, v67
	v_rcp_f32_e32 v64, v64
	v_rcp_f32_e32 v65, v65
	v_rcp_f32_e32 v66, v66
	v_rcp_f32_e32 v67, v67
	s_nop 0
	v_cvt_pk_f16_f32 v64, v64, v65
	v_cvt_pk_f16_f32 v65, v66, v67
	global_store_dwordx2 v136, v[64:65], s[4:5] offset:-736
	v_add_f32_e32 v60, v60, v142
	v_add_f32_e32 v61, v61, v143
	v_add_f32_e32 v62, v62, v144
	v_add_f32_e32 v63, v63, v145
	v_mul_f32_e32 v60, 0xbfb8aa3b, v60
	v_mul_f32_e32 v61, 0xbfb8aa3b, v61
	v_mul_f32_e32 v62, 0xbfb8aa3b, v62
	v_mul_f32_e32 v63, 0xbfb8aa3b, v63
	v_exp_f32_e32 v60, v60
	v_exp_f32_e32 v61, v61
	v_exp_f32_e32 v62, v62
	v_exp_f32_e32 v63, v63
	v_add_f32_e32 v60, 1.0, v60
	v_add_f32_e32 v61, 1.0, v61
	v_add_f32_e32 v62, 1.0, v62
	v_add_f32_e32 v63, 1.0, v63
	v_rcp_f32_e32 v60, v60
	v_rcp_f32_e32 v61, v61
	v_rcp_f32_e32 v62, v62
	v_rcp_f32_e32 v63, v63
	s_nop 0
	v_cvt_pk_f16_f32 v60, v60, v61
	v_cvt_pk_f16_f32 v61, v62, v63
	global_store_dwordx2 v137, v[60:61], s[4:5] offset:-1024
	v_add_f32_e32 v56, v56, v146
	v_add_f32_e32 v57, v57, v147
	v_add_f32_e32 v58, v58, v148
	v_add_f32_e32 v59, v59, v149
	v_mul_f32_e32 v56, 0xbfb8aa3b, v56
	v_mul_f32_e32 v57, 0xbfb8aa3b, v57
	v_mul_f32_e32 v58, 0xbfb8aa3b, v58
	v_mul_f32_e32 v59, 0xbfb8aa3b, v59
	v_exp_f32_e32 v56, v56
	v_exp_f32_e32 v57, v57
	v_exp_f32_e32 v58, v58
	v_exp_f32_e32 v59, v59
	v_add_f32_e32 v56, 1.0, v56
	v_add_f32_e32 v57, 1.0, v57
	v_add_f32_e32 v58, 1.0, v58
	v_add_f32_e32 v59, 1.0, v59
	v_rcp_f32_e32 v56, v56
	v_rcp_f32_e32 v57, v57
	v_rcp_f32_e32 v58, v58
	v_rcp_f32_e32 v59, v59
	s_nop 0
	v_cvt_pk_f16_f32 v56, v56, v57
	v_cvt_pk_f16_f32 v57, v58, v59
	global_store_dwordx2 v137, v[56:57], s[4:5] offset:-992
	v_add_f32_e32 v52, v52, v142
	v_add_f32_e32 v53, v53, v143
	v_add_f32_e32 v54, v54, v144
	v_add_f32_e32 v55, v55, v145
	v_mul_f32_e32 v52, 0xbfb8aa3b, v52
	v_mul_f32_e32 v53, 0xbfb8aa3b, v53
	v_mul_f32_e32 v54, 0xbfb8aa3b, v54
	v_mul_f32_e32 v55, 0xbfb8aa3b, v55
	v_exp_f32_e32 v52, v52
	v_exp_f32_e32 v53, v53
	v_exp_f32_e32 v54, v54
	v_exp_f32_e32 v55, v55
	v_add_f32_e32 v52, 1.0, v52
	v_add_f32_e32 v53, 1.0, v53
	v_add_f32_e32 v54, 1.0, v54
	v_add_f32_e32 v55, 1.0, v55
	v_rcp_f32_e32 v52, v52
	v_rcp_f32_e32 v53, v53
	v_rcp_f32_e32 v54, v54
	v_rcp_f32_e32 v55, v55
	s_nop 0
	v_cvt_pk_f16_f32 v52, v52, v53
	v_cvt_pk_f16_f32 v53, v54, v55
	global_store_dwordx2 v138, v[52:53], s[4:5] offset:-1024
	v_add_f32_e32 v48, v48, v146
	v_add_f32_e32 v49, v49, v147
	v_add_f32_e32 v50, v50, v148
	v_add_f32_e32 v51, v51, v149
	v_mul_f32_e32 v48, 0xbfb8aa3b, v48
	v_mul_f32_e32 v49, 0xbfb8aa3b, v49
	v_mul_f32_e32 v50, 0xbfb8aa3b, v50
	v_mul_f32_e32 v51, 0xbfb8aa3b, v51
	v_exp_f32_e32 v48, v48
	v_exp_f32_e32 v49, v49
	v_exp_f32_e32 v50, v50
	v_exp_f32_e32 v51, v51
	v_add_f32_e32 v48, 1.0, v48
	v_add_f32_e32 v49, 1.0, v49
	v_add_f32_e32 v50, 1.0, v50
	v_add_f32_e32 v51, 1.0, v51
	v_rcp_f32_e32 v48, v48
	v_rcp_f32_e32 v49, v49
	v_rcp_f32_e32 v50, v50
	v_rcp_f32_e32 v51, v51
	s_nop 0
	v_cvt_pk_f16_f32 v48, v48, v49
	v_cvt_pk_f16_f32 v49, v50, v51
	global_store_dwordx2 v138, v[48:49], s[4:5] offset:-992
	v_add_f32_e32 v44, v44, v142
	v_add_f32_e32 v45, v45, v143
	v_add_f32_e32 v46, v46, v144
	v_add_f32_e32 v47, v47, v145
	v_mul_f32_e32 v44, 0xbfb8aa3b, v44
	v_mul_f32_e32 v45, 0xbfb8aa3b, v45
	v_mul_f32_e32 v46, 0xbfb8aa3b, v46
	v_mul_f32_e32 v47, 0xbfb8aa3b, v47
	v_exp_f32_e32 v44, v44
	v_exp_f32_e32 v45, v45
	v_exp_f32_e32 v46, v46
	v_exp_f32_e32 v47, v47
	v_add_f32_e32 v44, 1.0, v44
	v_add_f32_e32 v45, 1.0, v45
	v_add_f32_e32 v46, 1.0, v46
	v_add_f32_e32 v47, 1.0, v47
	v_rcp_f32_e32 v44, v44
	v_rcp_f32_e32 v45, v45
	v_rcp_f32_e32 v46, v46
	v_rcp_f32_e32 v47, v47
	s_nop 0
	v_cvt_pk_f16_f32 v44, v44, v45
	v_cvt_pk_f16_f32 v45, v46, v47
	global_store_dwordx2 v139, v[44:45], s[4:5] offset:-1024
	v_add_f32_e32 v40, v40, v146
	v_add_f32_e32 v41, v41, v147
	v_add_f32_e32 v42, v42, v148
	v_add_f32_e32 v43, v43, v149
	v_mul_f32_e32 v40, 0xbfb8aa3b, v40
	v_mul_f32_e32 v41, 0xbfb8aa3b, v41
	v_mul_f32_e32 v42, 0xbfb8aa3b, v42
	v_mul_f32_e32 v43, 0xbfb8aa3b, v43
	v_exp_f32_e32 v40, v40
	v_exp_f32_e32 v41, v41
	v_exp_f32_e32 v42, v42
	v_exp_f32_e32 v43, v43
	v_add_f32_e32 v40, 1.0, v40
	v_add_f32_e32 v41, 1.0, v41
	v_add_f32_e32 v42, 1.0, v42
	v_add_f32_e32 v43, 1.0, v43
	v_rcp_f32_e32 v40, v40
	v_rcp_f32_e32 v41, v41
	v_rcp_f32_e32 v42, v42
	v_rcp_f32_e32 v43, v43
	s_nop 0
	v_cvt_pk_f16_f32 v40, v40, v41
	v_cvt_pk_f16_f32 v41, v42, v43
	global_store_dwordx2 v139, v[40:41], s[4:5] offset:-992
	v_add_f32_e32 v36, v36, v142
	v_add_f32_e32 v37, v37, v143
	v_add_f32_e32 v38, v38, v144
	v_add_f32_e32 v39, v39, v145
	v_mul_f32_e32 v36, 0xbfb8aa3b, v36
	v_mul_f32_e32 v37, 0xbfb8aa3b, v37
	v_mul_f32_e32 v38, 0xbfb8aa3b, v38
	v_mul_f32_e32 v39, 0xbfb8aa3b, v39
	v_exp_f32_e32 v36, v36
	v_exp_f32_e32 v37, v37
	v_exp_f32_e32 v38, v38
	v_exp_f32_e32 v39, v39
	v_add_f32_e32 v36, 1.0, v36
	v_add_f32_e32 v37, 1.0, v37
	v_add_f32_e32 v38, 1.0, v38
	v_add_f32_e32 v39, 1.0, v39
	v_rcp_f32_e32 v36, v36
	v_rcp_f32_e32 v37, v37
	v_rcp_f32_e32 v38, v38
	v_rcp_f32_e32 v39, v39
	s_nop 0
	v_cvt_pk_f16_f32 v36, v36, v37
	v_cvt_pk_f16_f32 v37, v38, v39
	global_store_dwordx2 v140, v[36:37], s[4:5] offset:-1024
	v_add_f32_e32 v32, v32, v146
	v_add_f32_e32 v33, v33, v147
	v_add_f32_e32 v34, v34, v148
	v_add_f32_e32 v35, v35, v149
	v_mul_f32_e32 v32, 0xbfb8aa3b, v32
	v_mul_f32_e32 v33, 0xbfb8aa3b, v33
	v_mul_f32_e32 v34, 0xbfb8aa3b, v34
	v_mul_f32_e32 v35, 0xbfb8aa3b, v35
	v_exp_f32_e32 v32, v32
	v_exp_f32_e32 v33, v33
	v_exp_f32_e32 v34, v34
	v_exp_f32_e32 v35, v35
	v_add_f32_e32 v32, 1.0, v32
	v_add_f32_e32 v33, 1.0, v33
	v_add_f32_e32 v34, 1.0, v34
	v_add_f32_e32 v35, 1.0, v35
	v_rcp_f32_e32 v32, v32
	v_rcp_f32_e32 v33, v33
	v_rcp_f32_e32 v34, v34
	v_rcp_f32_e32 v35, v35
	s_nop 0
	v_cvt_pk_f16_f32 v32, v32, v33
	v_cvt_pk_f16_f32 v33, v34, v35
	global_store_dwordx2 v140, v[32:33], s[4:5] offset:-992
	v_add_f32_e32 v28, v28, v150
	v_add_f32_e32 v29, v29, v151
	v_add_f32_e32 v30, v30, v152
	v_add_f32_e32 v31, v31, v153
	v_mul_f32_e32 v28, 0xbfb8aa3b, v28
	v_mul_f32_e32 v29, 0xbfb8aa3b, v29
	v_mul_f32_e32 v30, 0xbfb8aa3b, v30
	v_mul_f32_e32 v31, 0xbfb8aa3b, v31
	v_exp_f32_e32 v28, v28
	v_exp_f32_e32 v29, v29
	v_exp_f32_e32 v30, v30
	v_exp_f32_e32 v31, v31
	v_add_f32_e32 v28, 1.0, v28
	v_add_f32_e32 v29, 1.0, v29
	v_add_f32_e32 v30, 1.0, v30
	v_add_f32_e32 v31, 1.0, v31
	v_rcp_f32_e32 v28, v28
	v_rcp_f32_e32 v29, v29
	v_rcp_f32_e32 v30, v30
	v_rcp_f32_e32 v31, v31
	s_nop 0
	v_cvt_pk_f16_f32 v28, v28, v29
	v_cvt_pk_f16_f32 v29, v30, v31
	global_store_dwordx2 v137, v[28:29], s[4:5] offset:-768
	v_add_f32_e32 v24, v24, v154
	v_add_f32_e32 v25, v25, v155
	v_add_f32_e32 v26, v26, v156
	v_add_f32_e32 v27, v27, v157
	v_mul_f32_e32 v24, 0xbfb8aa3b, v24
	v_mul_f32_e32 v25, 0xbfb8aa3b, v25
	v_mul_f32_e32 v26, 0xbfb8aa3b, v26
	v_mul_f32_e32 v27, 0xbfb8aa3b, v27
	v_exp_f32_e32 v24, v24
	v_exp_f32_e32 v25, v25
	v_exp_f32_e32 v26, v26
	v_exp_f32_e32 v27, v27
	v_add_f32_e32 v24, 1.0, v24
	v_add_f32_e32 v25, 1.0, v25
	v_add_f32_e32 v26, 1.0, v26
	v_add_f32_e32 v27, 1.0, v27
	v_rcp_f32_e32 v24, v24
	v_rcp_f32_e32 v25, v25
	v_rcp_f32_e32 v26, v26
	v_rcp_f32_e32 v27, v27
	s_nop 0
	v_cvt_pk_f16_f32 v24, v24, v25
	v_cvt_pk_f16_f32 v25, v26, v27
	global_store_dwordx2 v137, v[24:25], s[4:5] offset:-736
	v_add_f32_e32 v20, v20, v150
	v_add_f32_e32 v21, v21, v151
	v_add_f32_e32 v22, v22, v152
	v_add_f32_e32 v23, v23, v153
	v_mul_f32_e32 v20, 0xbfb8aa3b, v20
	v_mul_f32_e32 v21, 0xbfb8aa3b, v21
	v_mul_f32_e32 v22, 0xbfb8aa3b, v22
	v_mul_f32_e32 v23, 0xbfb8aa3b, v23
	v_exp_f32_e32 v20, v20
	v_exp_f32_e32 v21, v21
	v_exp_f32_e32 v22, v22
	v_exp_f32_e32 v23, v23
	v_add_f32_e32 v20, 1.0, v20
	v_add_f32_e32 v21, 1.0, v21
	v_add_f32_e32 v22, 1.0, v22
	v_add_f32_e32 v23, 1.0, v23
	v_rcp_f32_e32 v20, v20
	v_rcp_f32_e32 v21, v21
	v_rcp_f32_e32 v22, v22
	v_rcp_f32_e32 v23, v23
	s_nop 0
	v_cvt_pk_f16_f32 v20, v20, v21
	v_cvt_pk_f16_f32 v21, v22, v23
	global_store_dwordx2 v138, v[20:21], s[4:5] offset:-768
	v_add_f32_e32 v16, v16, v154
	v_add_f32_e32 v17, v17, v155
	v_add_f32_e32 v18, v18, v156
	v_add_f32_e32 v19, v19, v157
	v_mul_f32_e32 v16, 0xbfb8aa3b, v16
	v_mul_f32_e32 v17, 0xbfb8aa3b, v17
	v_mul_f32_e32 v18, 0xbfb8aa3b, v18
	v_mul_f32_e32 v19, 0xbfb8aa3b, v19
	v_exp_f32_e32 v16, v16
	v_exp_f32_e32 v17, v17
	v_exp_f32_e32 v18, v18
	v_exp_f32_e32 v19, v19
	v_add_f32_e32 v16, 1.0, v16
	v_add_f32_e32 v17, 1.0, v17
	v_add_f32_e32 v18, 1.0, v18
	v_add_f32_e32 v19, 1.0, v19
	v_rcp_f32_e32 v16, v16
	v_rcp_f32_e32 v17, v17
	v_rcp_f32_e32 v18, v18
	v_rcp_f32_e32 v19, v19
	s_nop 0
	v_cvt_pk_f16_f32 v16, v16, v17
	v_cvt_pk_f16_f32 v17, v18, v19
	global_store_dwordx2 v138, v[16:17], s[4:5] offset:-736
	v_add_f32_e32 v12, v12, v150
	v_add_f32_e32 v13, v13, v151
	v_add_f32_e32 v14, v14, v152
	v_add_f32_e32 v15, v15, v153
	v_mul_f32_e32 v12, 0xbfb8aa3b, v12
	v_mul_f32_e32 v13, 0xbfb8aa3b, v13
	v_mul_f32_e32 v14, 0xbfb8aa3b, v14
	v_mul_f32_e32 v15, 0xbfb8aa3b, v15
	v_exp_f32_e32 v12, v12
	v_exp_f32_e32 v13, v13
	v_exp_f32_e32 v14, v14
	v_exp_f32_e32 v15, v15
	v_add_f32_e32 v12, 1.0, v12
	v_add_f32_e32 v13, 1.0, v13
	v_add_f32_e32 v14, 1.0, v14
	v_add_f32_e32 v15, 1.0, v15
	v_rcp_f32_e32 v12, v12
	v_rcp_f32_e32 v13, v13
	v_rcp_f32_e32 v14, v14
	v_rcp_f32_e32 v15, v15
	s_nop 0
	v_cvt_pk_f16_f32 v12, v12, v13
	v_cvt_pk_f16_f32 v13, v14, v15
	global_store_dwordx2 v139, v[12:13], s[4:5] offset:-768
	v_add_f32_e32 v8, v8, v154
	v_add_f32_e32 v9, v9, v155
	v_add_f32_e32 v10, v10, v156
	v_add_f32_e32 v11, v11, v157
	v_mul_f32_e32 v8, 0xbfb8aa3b, v8
	v_mul_f32_e32 v9, 0xbfb8aa3b, v9
	v_mul_f32_e32 v10, 0xbfb8aa3b, v10
	v_mul_f32_e32 v11, 0xbfb8aa3b, v11
	v_exp_f32_e32 v8, v8
	v_exp_f32_e32 v9, v9
	v_exp_f32_e32 v10, v10
	v_exp_f32_e32 v11, v11
	v_add_f32_e32 v8, 1.0, v8
	v_add_f32_e32 v9, 1.0, v9
	v_add_f32_e32 v10, 1.0, v10
	v_add_f32_e32 v11, 1.0, v11
	v_rcp_f32_e32 v8, v8
	v_rcp_f32_e32 v9, v9
	v_rcp_f32_e32 v10, v10
	v_rcp_f32_e32 v11, v11
	s_nop 0
	v_cvt_pk_f16_f32 v8, v8, v9
	v_cvt_pk_f16_f32 v9, v10, v11
	global_store_dwordx2 v139, v[8:9], s[4:5] offset:-736
	v_add_f32_e32 v4, v4, v150
	v_add_f32_e32 v5, v5, v151
	v_add_f32_e32 v6, v6, v152
	v_add_f32_e32 v7, v7, v153
	v_mul_f32_e32 v4, 0xbfb8aa3b, v4
	v_mul_f32_e32 v5, 0xbfb8aa3b, v5
	v_mul_f32_e32 v6, 0xbfb8aa3b, v6
	v_mul_f32_e32 v7, 0xbfb8aa3b, v7
	v_exp_f32_e32 v4, v4
	v_exp_f32_e32 v5, v5
	v_exp_f32_e32 v6, v6
	v_exp_f32_e32 v7, v7
	v_add_f32_e32 v4, 1.0, v4
	v_add_f32_e32 v5, 1.0, v5
	v_add_f32_e32 v6, 1.0, v6
	v_add_f32_e32 v7, 1.0, v7
	v_rcp_f32_e32 v4, v4
	v_rcp_f32_e32 v5, v5
	v_rcp_f32_e32 v6, v6
	v_rcp_f32_e32 v7, v7
	s_nop 0
	v_cvt_pk_f16_f32 v4, v4, v5
	v_cvt_pk_f16_f32 v5, v6, v7
	global_store_dwordx2 v140, v[4:5], s[4:5] offset:-768
	v_add_f32_e32 v0, v0, v154
	v_add_f32_e32 v1, v1, v155
	v_add_f32_e32 v2, v2, v156
	v_add_f32_e32 v3, v3, v157
	v_mul_f32_e32 v0, 0xbfb8aa3b, v0
	v_mul_f32_e32 v1, 0xbfb8aa3b, v1
	v_mul_f32_e32 v2, 0xbfb8aa3b, v2
	v_mul_f32_e32 v3, 0xbfb8aa3b, v3
	v_exp_f32_e32 v0, v0
	v_exp_f32_e32 v1, v1
	v_exp_f32_e32 v2, v2
	v_exp_f32_e32 v3, v3
	v_add_f32_e32 v0, 1.0, v0
	v_add_f32_e32 v1, 1.0, v1
	v_add_f32_e32 v2, 1.0, v2
	v_add_f32_e32 v3, 1.0, v3
	v_rcp_f32_e32 v0, v0
	v_rcp_f32_e32 v1, v1
	v_rcp_f32_e32 v2, v2
	v_rcp_f32_e32 v3, v3
	s_nop 0
	v_cvt_pk_f16_f32 v0, v0, v1
	v_cvt_pk_f16_f32 v1, v2, v3
	global_store_dwordx2 v140, v[0:1], s[4:5] offset:-736
	s_branch .Llora_done
.Llora_g:
	v_cvt_pk_f16_f32 v124, v124, v125
	v_cvt_pk_f16_f32 v125, v126, v127
	global_store_dwordx2 v131, v[124:125], s[16:17] offset:-2048
	v_cvt_pk_f16_f32 v120, v120, v121
	v_cvt_pk_f16_f32 v121, v122, v123
	global_store_dwordx2 v131, v[120:121], s[16:17] offset:-2016
	v_cvt_pk_f16_f32 v116, v116, v117
	v_cvt_pk_f16_f32 v117, v118, v119
	global_store_dwordx2 v134, v[116:117], s[16:17] offset:-2048
	v_cvt_pk_f16_f32 v112, v112, v113
	v_cvt_pk_f16_f32 v113, v114, v115
	global_store_dwordx2 v134, v[112:113], s[16:17] offset:-2016
	v_cvt_pk_f16_f32 v108, v108, v109
	v_cvt_pk_f16_f32 v109, v110, v111
	global_store_dwordx2 v135, v[108:109], s[16:17] offset:-2048
	v_cvt_pk_f16_f32 v104, v104, v105
	v_cvt_pk_f16_f32 v105, v106, v107
	global_store_dwordx2 v135, v[104:105], s[16:17] offset:-2016
	v_cvt_pk_f16_f32 v100, v100, v101
	v_cvt_pk_f16_f32 v101, v102, v103
	global_store_dwordx2 v136, v[100:101], s[16:17] offset:-2048
	v_cvt_pk_f16_f32 v96, v96, v97
	v_cvt_pk_f16_f32 v97, v98, v99
	global_store_dwordx2 v136, v[96:97], s[16:17] offset:-2016
	v_cvt_pk_f16_f32 v92, v92, v93
	v_cvt_pk_f16_f32 v93, v94, v95
	global_store_dwordx2 v131, v[92:93], s[16:17] offset:-1792
	v_cvt_pk_f16_f32 v88, v88, v89
	v_cvt_pk_f16_f32 v89, v90, v91
	global_store_dwordx2 v131, v[88:89], s[16:17] offset:-1760
	v_cvt_pk_f16_f32 v84, v84, v85
	v_cvt_pk_f16_f32 v85, v86, v87
	global_store_dwordx2 v134, v[84:85], s[16:17] offset:-1792
	v_cvt_pk_f16_f32 v80, v80, v81
	v_cvt_pk_f16_f32 v81, v82, v83
	global_store_dwordx2 v134, v[80:81], s[16:17] offset:-1760
	v_cvt_pk_f16_f32 v76, v76, v77
	v_cvt_pk_f16_f32 v77, v78, v79
	global_store_dwordx2 v135, v[76:77], s[16:17] offset:-1792
	v_cvt_pk_f16_f32 v72, v72, v73
	v_cvt_pk_f16_f32 v73, v74, v75
	global_store_dwordx2 v135, v[72:73], s[16:17] offset:-1760
	v_cvt_pk_f16_f32 v68, v68, v69
	v_cvt_pk_f16_f32 v69, v70, v71
	global_store_dwordx2 v136, v[68:69], s[16:17] offset:-1792
	v_cvt_pk_f16_f32 v64, v64, v65
	v_cvt_pk_f16_f32 v65, v66, v67
	global_store_dwordx2 v136, v[64:65], s[16:17] offset:-1760
	v_cvt_pk_f16_f32 v60, v60, v61
	v_cvt_pk_f16_f32 v61, v62, v63
	global_store_dwordx2 v137, v[60:61], s[16:17] offset:-2048
	v_cvt_pk_f16_f32 v56, v56, v57
	v_cvt_pk_f16_f32 v57, v58, v59
	global_store_dwordx2 v137, v[56:57], s[16:17] offset:-2016
	v_cvt_pk_f16_f32 v52, v52, v53
	v_cvt_pk_f16_f32 v53, v54, v55
	global_store_dwordx2 v138, v[52:53], s[16:17] offset:-2048
	v_cvt_pk_f16_f32 v48, v48, v49
	v_cvt_pk_f16_f32 v49, v50, v51
	global_store_dwordx2 v138, v[48:49], s[16:17] offset:-2016
	v_cvt_pk_f16_f32 v44, v44, v45
	v_cvt_pk_f16_f32 v45, v46, v47
	global_store_dwordx2 v139, v[44:45], s[16:17] offset:-2048
	v_cvt_pk_f16_f32 v40, v40, v41
	v_cvt_pk_f16_f32 v41, v42, v43
	global_store_dwordx2 v139, v[40:41], s[16:17] offset:-2016
	v_cvt_pk_f16_f32 v36, v36, v37
	v_cvt_pk_f16_f32 v37, v38, v39
	global_store_dwordx2 v140, v[36:37], s[16:17] offset:-2048
	v_cvt_pk_f16_f32 v32, v32, v33
	v_cvt_pk_f16_f32 v33, v34, v35
	global_store_dwordx2 v140, v[32:33], s[16:17] offset:-2016
	v_cvt_pk_f16_f32 v28, v28, v29
	v_cvt_pk_f16_f32 v29, v30, v31
	global_store_dwordx2 v137, v[28:29], s[16:17] offset:-1792
	v_cvt_pk_f16_f32 v24, v24, v25
	v_cvt_pk_f16_f32 v25, v26, v27
	global_store_dwordx2 v137, v[24:25], s[16:17] offset:-1760
	v_cvt_pk_f16_f32 v20, v20, v21
	v_cvt_pk_f16_f32 v21, v22, v23
	global_store_dwordx2 v138, v[20:21], s[16:17] offset:-1792
	v_cvt_pk_f16_f32 v16, v16, v17
	v_cvt_pk_f16_f32 v17, v18, v19
	global_store_dwordx2 v138, v[16:17], s[16:17] offset:-1760
	v_cvt_pk_f16_f32 v12, v12, v13
	v_cvt_pk_f16_f32 v13, v14, v15
	global_store_dwordx2 v139, v[12:13], s[16:17] offset:-1792
	v_cvt_pk_f16_f32 v8, v8, v9
	v_cvt_pk_f16_f32 v9, v10, v11
	global_store_dwordx2 v139, v[8:9], s[16:17] offset:-1760
	v_cvt_pk_f16_f32 v4, v4, v5
	v_cvt_pk_f16_f32 v5, v6, v7
	global_store_dwordx2 v140, v[4:5], s[16:17] offset:-1792
	v_cvt_pk_f16_f32 v0, v0, v1
	v_cvt_pk_f16_f32 v1, v2, v3
	global_store_dwordx2 v140, v[0:1], s[16:17] offset:-1760
.Llora_done:
	v_mov_b64_e32 v[4:5], s[6:7]
	v_mov_b64_e32 v[2:3], s[86:87]
	s_waitcnt vmcnt(0)
	s_barrier
